# mixer A: mask-free score path for non-edge waves (wave-uniform dispatch); mixer B prologue loads issued together
# speedup vs baseline: 1.0253x; 1.0011x over previous
; __device__ __forceinline__ int crow(int i, int h) { return (i & 3) + 8 * (i >> 2) + 4 * h; }
; __device__ __forceinline__ void attnA_unit(LAS unsigned char* lds, const Args& A, int unit) {
;     ...
;                 const bool edge = (i0 < 64) || (i0 + 96 > L);
;                 float mxp[2] = {-1e30f, -1e30f};
; #pragma unroll
;                 for (int kt = 0; kt < 5; ++kt)
; #pragma unroll
;                     for (int i = 0; i < 16; ++i) {
;                         const int cr = crow(i, 0);
;                         float v = S[kt][i] * QK_C + bl[32 * kt + cr + 4 * hh - ql + 32];
;                         if (edge) { const int kidx = i0 - 64 + 32 * kt + cr + 4 * hh; if (kidx < 0 || kidx >= L) v = -1e30f; }
;                         S[kt][i] = v; mxp[i & 1] = fmaxf(mxp[i & 1], v);
;                     }
;                 float mx = fmaxf(mxp[0], mxp[1]);
;                 mx = fmaxf(mx, __shfl_xor(mx, 32));
.LBB0_301:
	ds_read2_b32 v[166:167], v157 offset0:32 offset1:33
	ds_read2_b32 v[168:169], v157 offset0:34 offset1:35
	v_cmp_gt_i32_e32 vcc, 64, v162
	v_cmp_lt_i32_e64 s[22:23], s99, v162
	v_add_u32_e32 v165, v162, v179
	s_or_b64 vcc, vcc, s[22:23]
	s_cmp_eq_u64 vcc, 0
	s_cbranch_scc1 .LmixA_fast
	v_cmp_lt_i32_e64 s[22:23], -1, v165
	v_cmp_gt_i32_e64 s[24:25], s87, v165
	s_waitcnt lgkmcnt(1)
	v_fmamk_f32 v64, v64, 0x3e38aa3b, v166
	s_and_b64 s[22:23], s[22:23], s[24:25]
	v_fmac_f32_e32 v167, 0x3e38aa3b, v65
	v_add_u32_e32 v65, 1, v165
	v_cndmask_b32_e64 v166, v221, v64, s[22:23]
	v_cmp_lt_i32_e64 s[22:23], -1, v65
	v_cmp_gt_i32_e64 s[24:25], s87, v65
	v_cndmask_b32_e32 v64, v64, v166, vcc
	s_and_b64 s[22:23], s[22:23], s[24:25]
	v_add_u32_e32 v166, 2, v165
	v_cndmask_b32_e64 v65, v221, v167, s[22:23]
	v_cmp_lt_i32_e64 s[22:23], -1, v166
	v_cmp_gt_i32_e64 s[24:25], s87, v166
	s_waitcnt lgkmcnt(0)
	v_fmamk_f32 v66, v66, 0x3e38aa3b, v168
	s_and_b64 s[22:23], s[22:23], s[24:25]
	v_cndmask_b32_e64 v166, v221, v66, s[22:23]
	v_cndmask_b32_e32 v65, v167, v65, vcc
	v_cndmask_b32_e32 v66, v66, v166, vcc
	ds_read2_b32 v[166:167], v157 offset0:40 offset1:41
	v_fmac_f32_e32 v169, 0x3e38aa3b, v67
	v_add_u32_e32 v67, 3, v165
	v_cmp_lt_i32_e64 s[22:23], -1, v67
	v_cmp_gt_i32_e64 s[24:25], s87, v67
	s_and_b64 s[22:23], s[22:23], s[24:25]
	v_cndmask_b32_e64 v67, v221, v169, s[22:23]
	v_cndmask_b32_e32 v67, v169, v67, vcc
	s_mov_b32 s22, 0xf149f2ca
	ds_read2_b32 v[168:169], v157 offset0:42 offset1:43
	s_waitcnt lgkmcnt(1)
	v_fmamk_f32 v68, v68, 0x3e38aa3b, v166
	v_add_u32_e32 v166, 8, v165
	v_max3_f32 v171, v65, s22, v67
	v_cmp_lt_i32_e64 s[22:23], -1, v166
	v_cmp_gt_i32_e64 s[24:25], s87, v166
	s_and_b64 s[22:23], s[22:23], s[24:25]
	v_fmac_f32_e32 v167, 0x3e38aa3b, v69
	v_add_u32_e32 v69, 9, v165
	v_cndmask_b32_e64 v166, v221, v68, s[22:23]
	v_cmp_lt_i32_e64 s[22:23], -1, v69
	v_cmp_gt_i32_e64 s[24:25], s87, v69
	v_cndmask_b32_e32 v68, v68, v166, vcc
	s_and_b64 s[22:23], s[22:23], s[24:25]
	v_add_u32_e32 v166, 10, v165
	v_cndmask_b32_e64 v69, v221, v167, s[22:23]
	v_cmp_lt_i32_e64 s[22:23], -1, v166
	v_cmp_gt_i32_e64 s[24:25], s87, v166
	s_waitcnt lgkmcnt(0)
	v_fmamk_f32 v70, v70, 0x3e38aa3b, v168
	s_and_b64 s[22:23], s[22:23], s[24:25]
	v_cndmask_b32_e64 v166, v221, v70, s[22:23]
	v_cndmask_b32_e32 v69, v167, v69, vcc
	v_cndmask_b32_e32 v70, v70, v166, vcc
	ds_read2_b32 v[166:167], v157 offset0:48 offset1:49
	v_fmac_f32_e32 v169, 0x3e38aa3b, v71
	v_add_u32_e32 v71, 11, v165
	v_cmp_lt_i32_e64 s[22:23], -1, v71
	v_cmp_gt_i32_e64 s[24:25], s87, v71
	s_and_b64 s[22:23], s[22:23], s[24:25]
	v_cndmask_b32_e64 v71, v221, v169, s[22:23]
	v_cndmask_b32_e32 v71, v169, v71, vcc
	ds_read2_b32 v[168:169], v157 offset0:50 offset1:51
	s_waitcnt lgkmcnt(1)
	v_fmamk_f32 v72, v72, 0x3e38aa3b, v166
	v_add_u32_e32 v166, 16, v165
	v_cmp_lt_i32_e64 s[22:23], -1, v166
	v_cmp_gt_i32_e64 s[24:25], s87, v166
	s_and_b64 s[22:23], s[22:23], s[24:25]
	v_fmac_f32_e32 v167, 0x3e38aa3b, v73
	v_add_u32_e32 v73, 17, v165
	v_cndmask_b32_e64 v166, v221, v72, s[22:23]
	v_cmp_lt_i32_e64 s[22:23], -1, v73
	v_cmp_gt_i32_e64 s[24:25], s87, v73
	v_cndmask_b32_e32 v72, v72, v166, vcc
	s_and_b64 s[22:23], s[22:23], s[24:25]
	v_add_u32_e32 v166, 18, v165
	v_cndmask_b32_e64 v73, v221, v167, s[22:23]
	v_cmp_lt_i32_e64 s[22:23], -1, v166
	v_cmp_gt_i32_e64 s[24:25], s87, v166
	s_waitcnt lgkmcnt(0)
	v_fmamk_f32 v74, v74, 0x3e38aa3b, v168
	s_and_b64 s[22:23], s[22:23], s[24:25]
	v_cndmask_b32_e64 v166, v221, v74, s[22:23]
	v_cndmask_b32_e32 v73, v167, v73, vcc
	v_cndmask_b32_e32 v74, v74, v166, vcc
	ds_read2_b32 v[166:167], v157 offset0:56 offset1:57
	v_fmac_f32_e32 v169, 0x3e38aa3b, v75
	v_add_u32_e32 v75, 19, v165
	v_cmp_lt_i32_e64 s[22:23], -1, v75
	v_cmp_gt_i32_e64 s[24:25], s87, v75
	s_and_b64 s[22:23], s[22:23], s[24:25]
	v_cndmask_b32_e64 v75, v221, v169, s[22:23]
	v_cndmask_b32_e32 v168, v169, v75, vcc
	s_waitcnt lgkmcnt(0)
	v_fmamk_f32 v75, v76, 0x3e38aa3b, v166
	v_add_u32_e32 v76, 24, v165
	v_cmp_lt_i32_e64 s[22:23], -1, v76
	v_cmp_gt_i32_e64 s[24:25], s87, v76
	v_max_f32_e32 v170, 0xf149f2ca, v64
	s_and_b64 s[22:23], s[22:23], s[24:25]
	v_max3_f32 v170, v170, v66, v68
	v_cndmask_b32_e64 v76, v221, v75, s[22:23]
	v_max3_f32 v171, v171, v69, v71
	v_max3_f32 v170, v170, v70, v72
	v_cndmask_b32_e32 v75, v75, v76, vcc
	v_max3_f32 v169, v171, v73, v168
	v_max3_f32 v172, v170, v74, v75
	ds_read2_b32 v[170:171], v157 offset0:58 offset1:59
	v_add_u32_e32 v76, 25, v165
	v_cmp_lt_i32_e64 s[22:23], -1, v76
	v_cmp_gt_i32_e64 s[24:25], s87, v76
	v_fmac_f32_e32 v167, 0x3e38aa3b, v77
	s_and_b64 s[22:23], s[22:23], s[24:25]
	v_cndmask_b32_e64 v76, v221, v167, s[22:23]
	v_cndmask_b32_e32 v76, v167, v76, vcc
	ds_read2_b32 v[166:167], v157 offset0:64 offset1:65
	s_waitcnt lgkmcnt(1)
	v_fmamk_f32 v77, v78, 0x3e38aa3b, v170
	v_add_u32_e32 v78, 26, v165
	v_cmp_lt_i32_e64 s[22:23], -1, v78
	v_cmp_gt_i32_e64 s[24:25], s87, v78
	s_and_b64 s[22:23], s[22:23], s[24:25]
	v_cndmask_b32_e64 v78, v221, v77, s[22:23]
	v_cndmask_b32_e32 v77, v77, v78, vcc
	v_add_u32_e32 v78, 27, v165
	v_cmp_lt_i32_e64 s[22:23], -1, v78
	v_cmp_gt_i32_e64 s[24:25], s87, v78
	v_fmac_f32_e32 v171, 0x3e38aa3b, v79
	s_and_b64 s[22:23], s[22:23], s[24:25]
	v_cndmask_b32_e64 v78, v221, v171, s[22:23]
	s_waitcnt lgkmcnt(0)
; __device__ __forceinline__ int crow(int i, int h) { return (i & 3) + 8 * (i >> 2) + 4 * h; }
; __device__ __forceinline__ void attnA_unit(LAS unsigned char* lds, const Args& A, int unit) {
;     ...
;                 const bool edge = (i0 < 64) || (i0 + 96 > L);
;                 float mxp[2] = {-1e30f, -1e30f};
; #pragma unroll
;                 for (int kt = 0; kt < 5; ++kt)
; #pragma unroll
;                     for (int i = 0; i < 16; ++i) {
;                         const int cr = crow(i, 0);
;                         float v = S[kt][i] * QK_C + bl[32 * kt + cr + 4 * hh - ql + 32];
;                         if (edge) { const int kidx = i0 - 64 + 32 * kt + cr + 4 * hh; if (kidx < 0 || kidx >= L) v = -1e30f; }
;                         S[kt][i] = v; mxp[i & 1] = fmaxf(mxp[i & 1], v);
;                     }
;                 float mx = fmaxf(mxp[0], mxp[1]);
;                 mx = fmaxf(mx, __shfl_xor(mx, 32));
	v_fmamk_f32 v48, v48, 0x3e38aa3b, v166
	v_add_u32_e32 v166, 32, v165
	v_cndmask_b32_e32 v78, v171, v78, vcc
	v_cmp_lt_i32_e64 s[22:23], -1, v166
	v_cmp_gt_i32_e64 s[24:25], s87, v166
	ds_read2_b32 v[170:171], v157 offset0:66 offset1:67
	s_and_b64 s[22:23], s[22:23], s[24:25]
	v_fmac_f32_e32 v167, 0x3e38aa3b, v49
	v_add_u32_e32 v49, 33, v165
	v_cndmask_b32_e64 v166, v221, v48, s[22:23]
	v_cmp_lt_i32_e64 s[22:23], -1, v49
	v_cmp_gt_i32_e64 s[24:25], s87, v49
	v_cndmask_b32_e32 v48, v48, v166, vcc
	s_and_b64 s[22:23], s[22:23], s[24:25]
	v_add_u32_e32 v166, 34, v165
	v_cndmask_b32_e64 v49, v221, v167, s[22:23]
	v_cmp_lt_i32_e64 s[22:23], -1, v166
	v_cmp_gt_i32_e64 s[24:25], s87, v166
	s_waitcnt lgkmcnt(0)
	v_fmamk_f32 v50, v50, 0x3e38aa3b, v170
	s_and_b64 s[22:23], s[22:23], s[24:25]
	v_cndmask_b32_e64 v166, v221, v50, s[22:23]
	v_cndmask_b32_e32 v49, v167, v49, vcc
	v_cndmask_b32_e32 v50, v50, v166, vcc
	ds_read2_b32 v[166:167], v157 offset0:72 offset1:73
	v_fmac_f32_e32 v171, 0x3e38aa3b, v51
	v_add_u32_e32 v51, 35, v165
	v_cmp_lt_i32_e64 s[22:23], -1, v51
	v_cmp_gt_i32_e64 s[24:25], s87, v51
	s_and_b64 s[22:23], s[22:23], s[24:25]
	v_cndmask_b32_e64 v51, v221, v171, s[22:23]
	v_cndmask_b32_e32 v51, v171, v51, vcc
	ds_read2_b32 v[170:171], v157 offset0:74 offset1:75
	s_waitcnt lgkmcnt(1)
	v_fmamk_f32 v52, v52, 0x3e38aa3b, v166
	v_add_u32_e32 v166, 40, v165
	v_cmp_lt_i32_e64 s[22:23], -1, v166
	v_cmp_gt_i32_e64 s[24:25], s87, v166
	s_and_b64 s[22:23], s[22:23], s[24:25]
	v_fmac_f32_e32 v167, 0x3e38aa3b, v53
	v_add_u32_e32 v53, 41, v165
	v_cndmask_b32_e64 v166, v221, v52, s[22:23]
	v_cmp_lt_i32_e64 s[22:23], -1, v53
	v_cmp_gt_i32_e64 s[24:25], s87, v53
	v_cndmask_b32_e32 v52, v52, v166, vcc
	s_and_b64 s[22:23], s[22:23], s[24:25]
	v_add_u32_e32 v166, 42, v165
	v_cndmask_b32_e64 v53, v221, v167, s[22:23]
	v_cmp_lt_i32_e64 s[22:23], -1, v166
	v_cmp_gt_i32_e64 s[24:25], s87, v166
	s_waitcnt lgkmcnt(0)
	v_fmamk_f32 v54, v54, 0x3e38aa3b, v170
	s_and_b64 s[22:23], s[22:23], s[24:25]
	v_cndmask_b32_e64 v166, v221, v54, s[22:23]
	v_cndmask_b32_e32 v53, v167, v53, vcc
	v_cndmask_b32_e32 v54, v54, v166, vcc
	ds_read2_b32 v[166:167], v157 offset0:80 offset1:81
	v_fmac_f32_e32 v171, 0x3e38aa3b, v55
	v_add_u32_e32 v55, 43, v165
	v_cmp_lt_i32_e64 s[22:23], -1, v55
	v_cmp_gt_i32_e64 s[24:25], s87, v55
	s_and_b64 s[22:23], s[22:23], s[24:25]
	v_cndmask_b32_e64 v55, v221, v171, s[22:23]
	v_cndmask_b32_e32 v55, v171, v55, vcc
	ds_read2_b32 v[170:171], v157 offset0:82 offset1:83
	s_waitcnt lgkmcnt(1)
	v_fmamk_f32 v56, v56, 0x3e38aa3b, v166
	v_add_u32_e32 v166, 48, v165
	v_cmp_lt_i32_e64 s[22:23], -1, v166
	v_cmp_gt_i32_e64 s[24:25], s87, v166
	s_and_b64 s[22:23], s[22:23], s[24:25]
	v_fmac_f32_e32 v167, 0x3e38aa3b, v57
	v_add_u32_e32 v57, 49, v165
	v_cndmask_b32_e64 v166, v221, v56, s[22:23]
	v_cmp_lt_i32_e64 s[22:23], -1, v57
	v_cmp_gt_i32_e64 s[24:25], s87, v57
	v_cndmask_b32_e32 v56, v56, v166, vcc
	s_and_b64 s[22:23], s[22:23], s[24:25]
	v_add_u32_e32 v166, 50, v165
	v_cndmask_b32_e64 v57, v221, v167, s[22:23]
	v_cmp_lt_i32_e64 s[22:23], -1, v166
	v_cmp_gt_i32_e64 s[24:25], s87, v166
	s_waitcnt lgkmcnt(0)
	v_fmamk_f32 v58, v58, 0x3e38aa3b, v170
	s_and_b64 s[22:23], s[22:23], s[24:25]
	v_cndmask_b32_e64 v166, v221, v58, s[22:23]
	v_cndmask_b32_e32 v57, v167, v57, vcc
	v_cndmask_b32_e32 v58, v58, v166, vcc
	ds_read2_b32 v[166:167], v157 offset0:88 offset1:89
	v_fmac_f32_e32 v171, 0x3e38aa3b, v59
	v_add_u32_e32 v59, 51, v165
	v_cmp_lt_i32_e64 s[22:23], -1, v59
	v_cmp_gt_i32_e64 s[24:25], s87, v59
	s_and_b64 s[22:23], s[22:23], s[24:25]
	v_cndmask_b32_e64 v59, v221, v171, s[22:23]
	v_cndmask_b32_e32 v59, v171, v59, vcc
	ds_read2_b32 v[170:171], v157 offset0:90 offset1:91
	s_waitcnt lgkmcnt(1)
	v_fmamk_f32 v60, v60, 0x3e38aa3b, v166
	v_add_u32_e32 v166, 56, v165
	v_cmp_lt_i32_e64 s[22:23], -1, v166
	v_cmp_gt_i32_e64 s[24:25], s87, v166
	s_and_b64 s[22:23], s[22:23], s[24:25]
	v_fmac_f32_e32 v167, 0x3e38aa3b, v61
	v_add_u32_e32 v61, 57, v165
	v_cndmask_b32_e64 v166, v221, v60, s[22:23]
	v_cmp_lt_i32_e64 s[22:23], -1, v61
	v_cmp_gt_i32_e64 s[24:25], s87, v61
	s_and_b64 s[22:23], s[22:23], s[24:25]
	v_cndmask_b32_e64 v61, v221, v167, s[22:23]
	v_cndmask_b32_e32 v61, v167, v61, vcc
	v_add_u32_e32 v167, 58, v165
	v_max3_f32 v79, v169, v76, v78
	v_max3_f32 v169, v172, v77, v48
	v_cmp_lt_i32_e64 s[22:23], -1, v167
	v_cmp_gt_i32_e64 s[24:25], s87, v167
	v_max3_f32 v169, v169, v50, v52
	s_waitcnt lgkmcnt(0)
	v_fmamk_f32 v62, v62, 0x3e38aa3b, v170
	s_and_b64 s[22:23], s[22:23], s[24:25]
	v_max3_f32 v169, v169, v54, v56
	v_cndmask_b32_e32 v60, v60, v166, vcc
	v_cndmask_b32_e64 v167, v221, v62, s[22:23]
	v_max3_f32 v166, v169, v58, v60
	v_cndmask_b32_e32 v169, v62, v167, vcc
	v_add_u32_e32 v62, 59, v165
	v_fmac_f32_e32 v171, 0x3e38aa3b, v63
	v_cmp_lt_i32_e64 s[22:23], -1, v62
	v_cmp_gt_i32_e64 s[24:25], s87, v62
	ds_read2_b32 v[62:63], v157 offset0:96 offset1:97
	s_and_b64 s[22:23], s[22:23], s[24:25]
	v_cndmask_b32_e64 v167, v221, v171, s[22:23]
	v_cndmask_b32_e32 v208, v171, v167, vcc
	v_max3_f32 v79, v79, v49, v51
	s_waitcnt lgkmcnt(0)
	v_fmamk_f32 v32, v32, 0x3e38aa3b, v62
	v_add_u32_e32 v62, 64, v165
	v_cmp_lt_i32_e64 s[22:23], -1, v62
	v_cmp_gt_i32_e64 s[24:25], s87, v62
	s_and_b64 s[22:23], s[22:23], s[24:25]
	v_cndmask_b32_e64 v62, v221, v32, s[22:23]
	v_cndmask_b32_e32 v209, v32, v62, vcc
	v_max3_f32 v32, v166, v169, v209
	ds_read2_b32 v[166:167], v157 offset0:98 offset1:99
	v_fmac_f32_e32 v63, 0x3e38aa3b, v33
	v_add_u32_e32 v33, 0x41, v165
	v_cmp_lt_i32_e64 s[22:23], -1, v33
	v_cmp_gt_i32_e64 s[24:25], s87, v33
	s_and_b64 s[22:23], s[22:23], s[24:25]
	v_cndmask_b32_e64 v33, v221, v63, s[22:23]
	v_cndmask_b32_e32 v210, v63, v33, vcc
	ds_read2_b32 v[62:63], v157 offset0:104 offset1:105
	s_waitcnt lgkmcnt(1)
; __device__ __forceinline__ int crow(int i, int h) { return (i & 3) + 8 * (i >> 2) + 4 * h; }
; __device__ __forceinline__ void attnA_unit(LAS unsigned char* lds, const Args& A, int unit) {
;     ...
;                 const bool edge = (i0 < 64) || (i0 + 96 > L);
;                 float mxp[2] = {-1e30f, -1e30f};
; #pragma unroll
;                 for (int kt = 0; kt < 5; ++kt)
; #pragma unroll
;                     for (int i = 0; i < 16; ++i) {
;                         const int cr = crow(i, 0);
;                         float v = S[kt][i] * QK_C + bl[32 * kt + cr + 4 * hh - ql + 32];
;                         if (edge) { const int kidx = i0 - 64 + 32 * kt + cr + 4 * hh; if (kidx < 0 || kidx >= L) v = -1e30f; }
;                         S[kt][i] = v; mxp[i & 1] = fmaxf(mxp[i & 1], v);
;                     }
;                 float mx = fmaxf(mxp[0], mxp[1]);
;                 mx = fmaxf(mx, __shfl_xor(mx, 32));
	v_fmamk_f32 v33, v34, 0x3e38aa3b, v166
	v_add_u32_e32 v34, 0x42, v165
	v_cmp_lt_i32_e64 s[22:23], -1, v34
	v_cmp_gt_i32_e64 s[24:25], s87, v34
	s_and_b64 s[22:23], s[22:23], s[24:25]
	v_cndmask_b32_e64 v34, v221, v33, s[22:23]
	v_cndmask_b32_e32 v33, v33, v34, vcc
	v_add_u32_e32 v34, 0x43, v165
	v_cmp_lt_i32_e64 s[22:23], -1, v34
	v_cmp_gt_i32_e64 s[24:25], s87, v34
	v_fmac_f32_e32 v167, 0x3e38aa3b, v35
	s_and_b64 s[22:23], s[22:23], s[24:25]
	s_waitcnt lgkmcnt(0)
	v_fmamk_f32 v35, v36, 0x3e38aa3b, v62
	v_add_u32_e32 v36, 0x48, v165
	v_cndmask_b32_e64 v34, v221, v167, s[22:23]
	v_cmp_lt_i32_e64 s[22:23], -1, v36
	v_cmp_gt_i32_e64 s[24:25], s87, v36
	s_and_b64 s[22:23], s[22:23], s[24:25]
	v_cndmask_b32_e32 v34, v167, v34, vcc
	v_cndmask_b32_e64 v36, v221, v35, s[22:23]
	ds_read2_b32 v[166:167], v157 offset0:106 offset1:107
	v_cndmask_b32_e32 v35, v35, v36, vcc
	v_add_u32_e32 v36, 0x49, v165
	v_cmp_lt_i32_e64 s[22:23], -1, v36
	v_cmp_gt_i32_e64 s[24:25], s87, v36
	v_fmac_f32_e32 v63, 0x3e38aa3b, v37
	s_and_b64 s[22:23], s[22:23], s[24:25]
	v_cndmask_b32_e64 v36, v221, v63, s[22:23]
	v_cndmask_b32_e32 v36, v63, v36, vcc
	ds_read2_b32 v[62:63], v157 offset0:112 offset1:113
	s_waitcnt lgkmcnt(1)
	v_fmamk_f32 v37, v38, 0x3e38aa3b, v166
	v_add_u32_e32 v38, 0x4a, v165
	v_cmp_lt_i32_e64 s[22:23], -1, v38
	v_cmp_gt_i32_e64 s[24:25], s87, v38
	s_and_b64 s[22:23], s[22:23], s[24:25]
	v_cndmask_b32_e64 v38, v221, v37, s[22:23]
	v_cndmask_b32_e32 v37, v37, v38, vcc
	v_add_u32_e32 v38, 0x4b, v165
	v_cmp_lt_i32_e64 s[22:23], -1, v38
	v_cmp_gt_i32_e64 s[24:25], s87, v38
	v_fmac_f32_e32 v167, 0x3e38aa3b, v39
	s_and_b64 s[22:23], s[22:23], s[24:25]
	s_waitcnt lgkmcnt(0)
	v_fmamk_f32 v39, v40, 0x3e38aa3b, v62
	v_add_u32_e32 v40, 0x50, v165
	v_cndmask_b32_e64 v38, v221, v167, s[22:23]
	v_cmp_lt_i32_e64 s[22:23], -1, v40
	v_cmp_gt_i32_e64 s[24:25], s87, v40
	s_and_b64 s[22:23], s[22:23], s[24:25]
	v_cndmask_b32_e32 v38, v167, v38, vcc
	v_cndmask_b32_e64 v40, v221, v39, s[22:23]
	ds_read2_b32 v[166:167], v157 offset0:114 offset1:115
	v_cndmask_b32_e32 v39, v39, v40, vcc
	v_add_u32_e32 v40, 0x51, v165
	v_cmp_lt_i32_e64 s[22:23], -1, v40
	v_cmp_gt_i32_e64 s[24:25], s87, v40
	v_fmac_f32_e32 v63, 0x3e38aa3b, v41
	s_and_b64 s[22:23], s[22:23], s[24:25]
	v_cndmask_b32_e64 v40, v221, v63, s[22:23]
	v_cndmask_b32_e32 v40, v63, v40, vcc
	ds_read2_b32 v[62:63], v157 offset0:120 offset1:121
	s_waitcnt lgkmcnt(1)
	v_fmamk_f32 v41, v42, 0x3e38aa3b, v166
	v_add_u32_e32 v42, 0x52, v165
	v_cmp_lt_i32_e64 s[22:23], -1, v42
	v_cmp_gt_i32_e64 s[24:25], s87, v42
	s_and_b64 s[22:23], s[22:23], s[24:25]
	v_cndmask_b32_e64 v42, v221, v41, s[22:23]
	v_cndmask_b32_e32 v41, v41, v42, vcc
	v_add_u32_e32 v42, 0x53, v165
	v_cmp_lt_i32_e64 s[22:23], -1, v42
	v_cmp_gt_i32_e64 s[24:25], s87, v42
	v_fmac_f32_e32 v167, 0x3e38aa3b, v43
	s_and_b64 s[22:23], s[22:23], s[24:25]
	s_waitcnt lgkmcnt(0)
	v_fmamk_f32 v43, v44, 0x3e38aa3b, v62
	v_add_u32_e32 v44, 0x58, v165
	v_cndmask_b32_e64 v42, v221, v167, s[22:23]
	v_cmp_lt_i32_e64 s[22:23], -1, v44
	v_cmp_gt_i32_e64 s[24:25], s87, v44
	s_and_b64 s[22:23], s[22:23], s[24:25]
	v_cndmask_b32_e32 v42, v167, v42, vcc
	v_cndmask_b32_e64 v44, v221, v43, s[22:23]
	ds_read2_b32 v[166:167], v157 offset0:122 offset1:123
	v_cndmask_b32_e32 v43, v43, v44, vcc
	v_add_u32_e32 v44, 0x59, v165
	v_cmp_lt_i32_e64 s[22:23], -1, v44
	v_cmp_gt_i32_e64 s[24:25], s87, v44
	v_fmac_f32_e32 v63, 0x3e38aa3b, v45
	s_and_b64 s[22:23], s[22:23], s[24:25]
	v_cndmask_b32_e64 v44, v221, v63, s[22:23]
	v_cndmask_b32_e32 v44, v63, v44, vcc
	ds_read2_b32 v[62:63], v157 offset0:128 offset1:129
	s_waitcnt lgkmcnt(1)
	v_fmamk_f32 v45, v46, 0x3e38aa3b, v166
	v_add_u32_e32 v46, 0x5a, v165
	v_cmp_lt_i32_e64 s[22:23], -1, v46
	v_cmp_gt_i32_e64 s[24:25], s87, v46
	s_and_b64 s[22:23], s[22:23], s[24:25]
	v_cndmask_b32_e64 v46, v221, v45, s[22:23]
	v_cndmask_b32_e32 v45, v45, v46, vcc
	v_add_u32_e32 v46, 0x5b, v165
	v_cmp_lt_i32_e64 s[22:23], -1, v46
	v_cmp_gt_i32_e64 s[24:25], s87, v46
	v_fmac_f32_e32 v167, 0x3e38aa3b, v47
	s_and_b64 s[22:23], s[22:23], s[24:25]
	v_cndmask_b32_e64 v46, v221, v167, s[22:23]
	s_waitcnt lgkmcnt(0)
	v_fmamk_f32 v16, v16, 0x3e38aa3b, v62
	v_add_u32_e32 v62, 0x60, v165
	v_cndmask_b32_e32 v46, v167, v46, vcc
	v_cmp_lt_i32_e64 s[22:23], -1, v62
	v_cmp_gt_i32_e64 s[24:25], s87, v62
	ds_read2_b32 v[166:167], v157 offset0:130 offset1:131
	s_and_b64 s[22:23], s[22:23], s[24:25]
	v_fmac_f32_e32 v63, 0x3e38aa3b, v17
	v_add_u32_e32 v17, 0x61, v165
	v_cndmask_b32_e64 v62, v221, v16, s[22:23]
	v_cmp_lt_i32_e64 s[22:23], -1, v17
	v_cmp_gt_i32_e64 s[24:25], s87, v17
	v_max3_f32 v79, v79, v53, v55
	v_cndmask_b32_e32 v16, v16, v62, vcc
	s_and_b64 s[22:23], s[22:23], s[24:25]
	v_add_u32_e32 v62, 0x62, v165
	v_max3_f32 v79, v79, v57, v59
	v_cndmask_b32_e64 v17, v221, v63, s[22:23]
	v_cmp_lt_i32_e64 s[22:23], -1, v62
	v_cmp_gt_i32_e64 s[24:25], s87, v62
	v_max3_f32 v79, v79, v61, v208
	s_waitcnt lgkmcnt(0)
	v_fmamk_f32 v18, v18, 0x3e38aa3b, v166
	s_and_b64 s[22:23], s[22:23], s[24:25]
	v_fmac_f32_e32 v167, 0x3e38aa3b, v19
	v_add_u32_e32 v19, 0x63, v165
	v_max3_f32 v79, v79, v210, v34
	v_cndmask_b32_e64 v62, v221, v18, s[22:23]
	v_cmp_lt_i32_e64 s[22:23], -1, v19
	v_cmp_gt_i32_e64 s[24:25], s87, v19
	v_max3_f32 v79, v79, v36, v38
	v_cndmask_b32_e32 v17, v63, v17, vcc
	v_cndmask_b32_e32 v18, v18, v62, vcc
	ds_read2_b32 v[62:63], v157 offset0:136 offset1:137
	s_and_b64 s[22:23], s[22:23], s[24:25]
	v_max3_f32 v79, v79, v40, v42
	v_cndmask_b32_e64 v19, v221, v167, s[22:23]
	v_max3_f32 v47, v79, v44, v46
	v_cndmask_b32_e32 v19, v167, v19, vcc
	v_max3_f32 v79, v47, v17, v19
	v_add_u32_e32 v47, 0x68, v165
	v_cmp_lt_i32_e64 s[22:23], -1, v47
	v_cmp_gt_i32_e64 s[24:25], s87, v47
	ds_read2_b32 v[166:167], v157 offset0:138 offset1:139
	s_waitcnt lgkmcnt(1)
; __device__ __forceinline__ int crow(int i, int h) { return (i & 3) + 8 * (i >> 2) + 4 * h; }
; __device__ __forceinline__ void attnA_unit(LAS unsigned char* lds, const Args& A, int unit) {
;     ...
;                 const bool edge = (i0 < 64) || (i0 + 96 > L);
;                 float mxp[2] = {-1e30f, -1e30f};
; #pragma unroll
;                 for (int kt = 0; kt < 5; ++kt)
; #pragma unroll
;                     for (int i = 0; i < 16; ++i) {
;                         const int cr = crow(i, 0);
;                         float v = S[kt][i] * QK_C + bl[32 * kt + cr + 4 * hh - ql + 32];
;                         if (edge) { const int kidx = i0 - 64 + 32 * kt + cr + 4 * hh; if (kidx < 0 || kidx >= L) v = -1e30f; }
;                         S[kt][i] = v; mxp[i & 1] = fmaxf(mxp[i & 1], v);
;                     }
;                 float mx = fmaxf(mxp[0], mxp[1]);
;                 mx = fmaxf(mx, __shfl_xor(mx, 32));
	v_fmamk_f32 v20, v20, 0x3e38aa3b, v62
	s_and_b64 s[22:23], s[22:23], s[24:25]
	v_fmac_f32_e32 v63, 0x3e38aa3b, v21
	v_add_u32_e32 v21, 0x69, v165
	v_cndmask_b32_e64 v47, v221, v20, s[22:23]
	v_cmp_lt_i32_e64 s[22:23], -1, v21
	v_cmp_gt_i32_e64 s[24:25], s87, v21
	s_and_b64 s[22:23], s[22:23], s[24:25]
	v_cndmask_b32_e64 v21, v221, v63, s[22:23]
	v_cndmask_b32_e32 v20, v20, v47, vcc
	v_cndmask_b32_e32 v47, v63, v21, vcc
	s_waitcnt lgkmcnt(0)
	v_fmamk_f32 v21, v22, 0x3e38aa3b, v166
	v_add_u32_e32 v22, 0x6a, v165
	v_cmp_lt_i32_e64 s[22:23], -1, v22
	v_cmp_gt_i32_e64 s[24:25], s87, v22
	s_and_b64 s[22:23], s[22:23], s[24:25]
	v_cndmask_b32_e64 v22, v221, v21, s[22:23]
	ds_read2_b32 v[62:63], v157 offset0:144 offset1:145
	v_cndmask_b32_e32 v211, v21, v22, vcc
	v_add_u32_e32 v21, 0x6b, v165
	v_cmp_lt_i32_e64 s[22:23], -1, v21
	v_cmp_gt_i32_e64 s[24:25], s87, v21
	v_fmac_f32_e32 v167, 0x3e38aa3b, v23
	s_and_b64 s[22:23], s[22:23], s[24:25]
	v_cndmask_b32_e64 v21, v221, v167, s[22:23]
	v_cndmask_b32_e32 v23, v167, v21, vcc
	ds_read2_b32 v[166:167], v157 offset0:146 offset1:147
	s_waitcnt lgkmcnt(1)
	v_fmamk_f32 v22, v24, 0x3e38aa3b, v62
	v_add_u32_e32 v24, 0x70, v165
	v_cmp_lt_i32_e64 s[22:23], -1, v24
	v_cmp_gt_i32_e64 s[24:25], s87, v24
	s_and_b64 s[22:23], s[22:23], s[24:25]
	v_cndmask_b32_e64 v24, v221, v22, s[22:23]
	v_cndmask_b32_e32 v22, v22, v24, vcc
	v_add_u32_e32 v24, 0x71, v165
	v_cmp_lt_i32_e64 s[22:23], -1, v24
	v_cmp_gt_i32_e64 s[24:25], s87, v24
	v_fmac_f32_e32 v63, 0x3e38aa3b, v25
	s_and_b64 s[22:23], s[22:23], s[24:25]
	s_waitcnt lgkmcnt(0)
	v_fmamk_f32 v25, v26, 0x3e38aa3b, v166
	v_add_u32_e32 v26, 0x72, v165
	v_cndmask_b32_e64 v24, v221, v63, s[22:23]
	v_cmp_lt_i32_e64 s[22:23], -1, v26
	v_cmp_gt_i32_e64 s[24:25], s87, v26
	s_and_b64 s[22:23], s[22:23], s[24:25]
	v_cndmask_b32_e64 v26, v221, v25, s[22:23]
	v_cndmask_b32_e32 v24, v63, v24, vcc
	v_cndmask_b32_e32 v25, v25, v26, vcc
	v_add_u32_e32 v26, 0x73, v165
	ds_read2_b32 v[62:63], v157 offset0:152 offset1:153
	v_cmp_lt_i32_e64 s[22:23], -1, v26
	v_cmp_gt_i32_e64 s[24:25], s87, v26
	v_fmac_f32_e32 v167, 0x3e38aa3b, v27
	s_and_b64 s[22:23], s[22:23], s[24:25]
	v_cndmask_b32_e64 v26, v221, v167, s[22:23]
	v_max3_f32 v21, v79, v47, v23
	v_cndmask_b32_e32 v27, v167, v26, vcc
	v_add_u32_e32 v26, 0x78, v165
	v_max3_f32 v79, v21, v24, v27
	s_waitcnt lgkmcnt(0)
	v_fmamk_f32 v21, v28, 0x3e38aa3b, v62
	v_cmp_lt_i32_e64 s[22:23], -1, v26
	v_cmp_gt_i32_e64 s[24:25], s87, v26
	v_fmac_f32_e32 v63, 0x3e38aa3b, v29
	ds_read2_b32 v[28:29], v157 offset0:154 offset1:155
	s_and_b64 s[22:23], s[22:23], s[24:25]
	v_cndmask_b32_e64 v26, v221, v21, s[22:23]
	v_cndmask_b32_e32 v21, v21, v26, vcc
	v_add_u32_e32 v26, 0x79, v165
	v_cmp_lt_i32_e64 s[22:23], -1, v26
	v_cmp_gt_i32_e64 s[24:25], s87, v26
	s_and_b64 s[22:23], s[22:23], s[24:25]
	s_waitcnt lgkmcnt(0)
	v_fmamk_f32 v28, v30, 0x3e38aa3b, v28
	v_add_u32_e32 v30, 0x7a, v165
	v_cndmask_b32_e64 v26, v221, v63, s[22:23]
	v_cmp_lt_i32_e64 s[22:23], -1, v30
	v_cmp_gt_i32_e64 s[24:25], s87, v30
	s_and_b64 s[22:23], s[22:23], s[24:25]
	v_cndmask_b32_e64 v30, v221, v28, s[22:23]
	v_cndmask_b32_e32 v28, v28, v30, vcc
	v_add_u32_e32 v30, 0x7b, v165
	v_fmac_f32_e32 v29, 0x3e38aa3b, v31
	v_cmp_lt_i32_e64 s[22:23], -1, v30
	v_cmp_gt_i32_e64 s[24:25], s87, v30
	ds_read2_b32 v[30:31], v157 offset0:160 offset1:161
	v_max3_f32 v32, v32, v33, v35
	s_and_b64 s[22:23], s[22:23], s[24:25]
	v_max3_f32 v32, v32, v37, v39
	v_cndmask_b32_e64 v62, v221, v29, s[22:23]
	s_waitcnt lgkmcnt(0)
	v_fmamk_f32 v0, v0, 0x3e38aa3b, v30
	v_add_u32_e32 v30, 0x80, v165
	v_cmp_lt_i32_e64 s[22:23], -1, v30
	v_cmp_gt_i32_e64 s[24:25], s87, v30
	v_max3_f32 v32, v32, v41, v43
	s_and_b64 s[22:23], s[22:23], s[24:25]
	v_max3_f32 v32, v32, v45, v16
	v_cndmask_b32_e64 v30, v221, v0, s[22:23]
	v_max3_f32 v32, v32, v18, v20
	v_cndmask_b32_e32 v223, v0, v30, vcc
	v_fmac_f32_e32 v31, 0x3e38aa3b, v1
	ds_read2_b32 v[0:1], v157 offset0:162 offset1:163
	v_max3_f32 v32, v32, v211, v22
	v_max3_f32 v32, v32, v25, v21
	v_max3_f32 v30, v32, v28, v223
	v_add_u32_e32 v32, 0x81, v165
	v_cmp_lt_i32_e64 s[22:23], -1, v32
	v_cmp_gt_i32_e64 s[24:25], s87, v32
	s_and_b64 s[22:23], s[22:23], s[24:25]
	s_waitcnt lgkmcnt(0)
	v_fmamk_f32 v0, v2, 0x3e38aa3b, v0
	v_add_u32_e32 v2, 0x82, v165
	v_cndmask_b32_e64 v32, v221, v31, s[22:23]
	v_cmp_lt_i32_e64 s[22:23], -1, v2
	v_cmp_gt_i32_e64 s[24:25], s87, v2
	s_and_b64 s[22:23], s[22:23], s[24:25]
	v_cndmask_b32_e64 v2, v221, v0, s[22:23]
	v_cndmask_b32_e32 v225, v0, v2, vcc
	v_add_u32_e32 v0, 0x83, v165
	v_fmac_f32_e32 v1, 0x3e38aa3b, v3
	v_cmp_lt_i32_e64 s[22:23], -1, v0
	v_cmp_gt_i32_e64 s[24:25], s87, v0
	ds_read2_b32 v[2:3], v157 offset0:168 offset1:169
	s_and_b64 s[22:23], s[22:23], s[24:25]
	v_cndmask_b32_e64 v0, v221, v1, s[22:23]
	v_cndmask_b32_e32 v227, v1, v0, vcc
	v_add_u32_e32 v1, 0x88, v165
	v_cmp_lt_i32_e64 s[22:23], -1, v1
	v_cmp_gt_i32_e64 s[24:25], s87, v1
	s_waitcnt lgkmcnt(0)
	v_fmamk_f32 v0, v4, 0x3e38aa3b, v2
	s_and_b64 s[22:23], s[22:23], s[24:25]
	v_cndmask_b32_e64 v1, v221, v0, s[22:23]
	v_add_u32_e32 v2, 0x89, v165
	v_cndmask_b32_e32 v228, v0, v1, vcc
	v_cmp_lt_i32_e64 s[22:23], -1, v2
	ds_read2_b32 v[0:1], v157 offset0:170 offset1:171
	v_cmp_gt_i32_e64 s[24:25], s87, v2
	v_fmac_f32_e32 v3, 0x3e38aa3b, v5
	s_and_b64 s[22:23], s[22:23], s[24:25]
	v_cndmask_b32_e64 v2, v221, v3, s[22:23]
	v_cndmask_b32_e32 v230, v3, v2, vcc
	v_add_u32_e32 v2, 0x8a, v165
	v_cmp_lt_i32_e64 s[22:23], -1, v2
	v_cmp_gt_i32_e64 s[24:25], s87, v2
	s_waitcnt lgkmcnt(0)
; __device__ __forceinline__ int crow(int i, int h) { return (i & 3) + 8 * (i >> 2) + 4 * h; }
; __device__ __forceinline__ void attnA_unit(LAS unsigned char* lds, const Args& A, int unit) {
;     ...
;                 const bool edge = (i0 < 64) || (i0 + 96 > L);
;                 float mxp[2] = {-1e30f, -1e30f};
; #pragma unroll
;                 for (int kt = 0; kt < 5; ++kt)
; #pragma unroll
;                     for (int i = 0; i < 16; ++i) {
;                         const int cr = crow(i, 0);
;                         float v = S[kt][i] * QK_C + bl[32 * kt + cr + 4 * hh - ql + 32];
;                         if (edge) { const int kidx = i0 - 64 + 32 * kt + cr + 4 * hh; if (kidx < 0 || kidx >= L) v = -1e30f; }
;                         S[kt][i] = v; mxp[i & 1] = fmaxf(mxp[i & 1], v);
;                     }
;                 float mx = fmaxf(mxp[0], mxp[1]);
;                 mx = fmaxf(mx, __shfl_xor(mx, 32));
	v_fmamk_f32 v0, v6, 0x3e38aa3b, v0
	s_and_b64 s[22:23], s[22:23], s[24:25]
	v_cndmask_b32_e64 v2, v221, v0, s[22:23]
	v_cndmask_b32_e32 v232, v0, v2, vcc
	v_add_u32_e32 v0, 0x8b, v165
	v_cmp_lt_i32_e64 s[22:23], -1, v0
	v_cmp_gt_i32_e64 s[24:25], s87, v0
	ds_read2_b32 v[2:3], v157 offset0:176 offset1:177
	v_fmac_f32_e32 v1, 0x3e38aa3b, v7
	s_and_b64 s[22:23], s[22:23], s[24:25]
	v_cndmask_b32_e64 v0, v221, v1, s[22:23]
	v_cndmask_b32_e32 v233, v1, v0, vcc
	v_add_u32_e32 v1, 0x90, v165
	v_cmp_lt_i32_e64 s[22:23], -1, v1
	v_cmp_gt_i32_e64 s[24:25], s87, v1
	s_waitcnt lgkmcnt(0)
	v_fmamk_f32 v0, v8, 0x3e38aa3b, v2
	s_and_b64 s[22:23], s[22:23], s[24:25]
	v_cndmask_b32_e64 v1, v221, v0, s[22:23]
	v_add_u32_e32 v2, 0x91, v165
	v_cndmask_b32_e32 v231, v0, v1, vcc
	v_cmp_lt_i32_e64 s[22:23], -1, v2
	ds_read2_b32 v[0:1], v157 offset0:178 offset1:179
	v_cmp_gt_i32_e64 s[24:25], s87, v2
	v_fmac_f32_e32 v3, 0x3e38aa3b, v9
	s_and_b64 s[22:23], s[22:23], s[24:25]
	v_cndmask_b32_e64 v2, v221, v3, s[22:23]
	v_cndmask_b32_e32 v234, v3, v2, vcc
	v_add_u32_e32 v2, 0x92, v165
	v_cmp_lt_i32_e64 s[22:23], -1, v2
	v_cmp_gt_i32_e64 s[24:25], s87, v2
	s_waitcnt lgkmcnt(0)
	v_fmamk_f32 v0, v10, 0x3e38aa3b, v0
	s_and_b64 s[22:23], s[22:23], s[24:25]
	v_cndmask_b32_e64 v2, v221, v0, s[22:23]
	v_cndmask_b32_e32 v235, v0, v2, vcc
	v_add_u32_e32 v0, 0x93, v165
	v_cmp_lt_i32_e64 s[22:23], -1, v0
	v_cmp_gt_i32_e64 s[24:25], s87, v0
	ds_read2_b32 v[2:3], v157 offset0:184 offset1:185
	v_fmac_f32_e32 v1, 0x3e38aa3b, v11
	s_and_b64 s[22:23], s[22:23], s[24:25]
	v_cndmask_b32_e64 v0, v221, v1, s[22:23]
	v_cndmask_b32_e32 v236, v1, v0, vcc
	v_add_u32_e32 v1, 0x98, v165
	v_cmp_lt_i32_e64 s[22:23], -1, v1
	v_cmp_gt_i32_e64 s[24:25], s87, v1
	s_waitcnt lgkmcnt(0)
	v_fmamk_f32 v0, v12, 0x3e38aa3b, v2
	s_and_b64 s[22:23], s[22:23], s[24:25]
	v_max3_f32 v4, v30, v225, v228
	v_cndmask_b32_e64 v1, v221, v0, s[22:23]
	v_max3_f32 v4, v4, v232, v231
	v_cndmask_b32_e32 v237, v0, v1, vcc
	v_max3_f32 v2, v4, v235, v237
	v_add_u32_e32 v4, 0x99, v165
	v_cmp_lt_i32_e64 s[22:23], -1, v4
	ds_read2_b32 v[0:1], v157 offset0:186 offset1:187
	v_cmp_gt_i32_e64 s[24:25], s87, v4
	v_fmac_f32_e32 v3, 0x3e38aa3b, v13
	s_and_b64 s[22:23], s[22:23], s[24:25]
	v_cndmask_b32_e64 v4, v221, v3, s[22:23]
	v_cndmask_b32_e32 v240, v3, v4, vcc
	v_add_u32_e32 v3, 0x9a, v165
	v_cmp_lt_i32_e64 s[22:23], -1, v3
	v_cmp_gt_i32_e64 s[24:25], s87, v3
	s_waitcnt lgkmcnt(0)
	v_fmamk_f32 v0, v14, 0x3e38aa3b, v0
	s_and_b64 s[22:23], s[22:23], s[24:25]
	v_cndmask_b32_e64 v3, v221, v0, s[22:23]
	v_cndmask_b32_e32 v26, v63, v26, vcc
	v_cndmask_b32_e32 v224, v29, v62, vcc
	v_cndmask_b32_e32 v239, v0, v3, vcc
	v_add_u32_e32 v0, 0x9b, v165
	v_max3_f32 v29, v79, v26, v224
	v_cndmask_b32_e32 v226, v31, v32, vcc
	v_cmp_lt_i32_e64 s[22:23], -1, v0
	v_cmp_gt_i32_e64 s[24:25], s87, v0
	v_max3_f32 v29, v29, v226, v227
	v_fmac_f32_e32 v1, 0x3e38aa3b, v15
	s_and_b64 s[22:23], s[22:23], s[24:25]
	v_max3_f32 v5, v29, v230, v233
	v_cndmask_b32_e64 v0, v221, v1, s[22:23]
	v_max3_f32 v5, v5, v234, v236
	v_cndmask_b32_e32 v241, v1, v0, vcc
	v_max3_f32 v0, v5, v240, v241
	v_max3_f32 v0, v2, v239, v0
	s_branch .LmixA_join
.LmixA_fast:
	s_waitcnt lgkmcnt(1)
	v_fmamk_f32 v64, v64, 0x3e38aa3b, v166
	v_fmac_f32_e32 v167, 0x3e38aa3b, v65
	s_waitcnt lgkmcnt(0)
	v_fmamk_f32 v66, v66, 0x3e38aa3b, v168
	v_mov_b32_e32 v65, v167
	ds_read2_b32 v[166:167], v157 offset0:40 offset1:41
	v_fmac_f32_e32 v169, 0x3e38aa3b, v67
	v_mov_b32_e32 v67, v169
	s_mov_b32 s22, 0xf149f2ca
	ds_read2_b32 v[168:169], v157 offset0:42 offset1:43
	s_waitcnt lgkmcnt(1)
	v_fmamk_f32 v68, v68, 0x3e38aa3b, v166
	v_max3_f32 v171, v65, s22, v67
	v_fmac_f32_e32 v167, 0x3e38aa3b, v69
	s_waitcnt lgkmcnt(0)
	v_fmamk_f32 v70, v70, 0x3e38aa3b, v168
	v_mov_b32_e32 v69, v167
	ds_read2_b32 v[166:167], v157 offset0:48 offset1:49
	v_fmac_f32_e32 v169, 0x3e38aa3b, v71
	v_mov_b32_e32 v71, v169
	ds_read2_b32 v[168:169], v157 offset0:50 offset1:51
	s_waitcnt lgkmcnt(1)
	v_fmamk_f32 v72, v72, 0x3e38aa3b, v166
	v_fmac_f32_e32 v167, 0x3e38aa3b, v73
	s_waitcnt lgkmcnt(0)
	v_fmamk_f32 v74, v74, 0x3e38aa3b, v168
	v_mov_b32_e32 v73, v167
	ds_read2_b32 v[166:167], v157 offset0:56 offset1:57
	v_fmac_f32_e32 v169, 0x3e38aa3b, v75
	v_mov_b32_e32 v168, v169
	s_waitcnt lgkmcnt(0)
	v_fmamk_f32 v75, v76, 0x3e38aa3b, v166
	v_max_f32_e32 v170, 0xf149f2ca, v64
	v_max3_f32 v170, v170, v66, v68
	v_max3_f32 v171, v171, v69, v71
	v_max3_f32 v170, v170, v70, v72
	v_max3_f32 v169, v171, v73, v168
	v_max3_f32 v172, v170, v74, v75
	ds_read2_b32 v[170:171], v157 offset0:58 offset1:59
	v_fmac_f32_e32 v167, 0x3e38aa3b, v77
	v_mov_b32_e32 v76, v167
	ds_read2_b32 v[166:167], v157 offset0:64 offset1:65
	s_waitcnt lgkmcnt(1)
	v_fmamk_f32 v77, v78, 0x3e38aa3b, v170
	v_fmac_f32_e32 v171, 0x3e38aa3b, v79
	s_waitcnt lgkmcnt(0)
	v_fmamk_f32 v48, v48, 0x3e38aa3b, v166
	v_mov_b32_e32 v78, v171
	ds_read2_b32 v[170:171], v157 offset0:66 offset1:67
	v_fmac_f32_e32 v167, 0x3e38aa3b, v49
	s_waitcnt lgkmcnt(0)
	v_fmamk_f32 v50, v50, 0x3e38aa3b, v170
	v_mov_b32_e32 v49, v167
	ds_read2_b32 v[166:167], v157 offset0:72 offset1:73
	v_fmac_f32_e32 v171, 0x3e38aa3b, v51
	v_mov_b32_e32 v51, v171
	ds_read2_b32 v[170:171], v157 offset0:74 offset1:75
	s_waitcnt lgkmcnt(1)
	v_fmamk_f32 v52, v52, 0x3e38aa3b, v166
	v_fmac_f32_e32 v167, 0x3e38aa3b, v53
	s_waitcnt lgkmcnt(0)
	v_fmamk_f32 v54, v54, 0x3e38aa3b, v170
	v_mov_b32_e32 v53, v167
	ds_read2_b32 v[166:167], v157 offset0:80 offset1:81
	v_fmac_f32_e32 v171, 0x3e38aa3b, v55
	v_mov_b32_e32 v55, v171
	ds_read2_b32 v[170:171], v157 offset0:82 offset1:83
	s_waitcnt lgkmcnt(1)
; __device__ __forceinline__ int crow(int i, int h) { return (i & 3) + 8 * (i >> 2) + 4 * h; }
; __device__ __forceinline__ void attnA_unit(LAS unsigned char* lds, const Args& A, int unit) {
;     ...
;                 const bool edge = (i0 < 64) || (i0 + 96 > L);
;                 float mxp[2] = {-1e30f, -1e30f};
; #pragma unroll
;                 for (int kt = 0; kt < 5; ++kt)
; #pragma unroll
;                     for (int i = 0; i < 16; ++i) {
;                         const int cr = crow(i, 0);
;                         float v = S[kt][i] * QK_C + bl[32 * kt + cr + 4 * hh - ql + 32];
;                         if (edge) { const int kidx = i0 - 64 + 32 * kt + cr + 4 * hh; if (kidx < 0 || kidx >= L) v = -1e30f; }
;                         S[kt][i] = v; mxp[i & 1] = fmaxf(mxp[i & 1], v);
;                     }
;                 float mx = fmaxf(mxp[0], mxp[1]);
;                 mx = fmaxf(mx, __shfl_xor(mx, 32));
	v_fmamk_f32 v56, v56, 0x3e38aa3b, v166
	v_fmac_f32_e32 v167, 0x3e38aa3b, v57
	s_waitcnt lgkmcnt(0)
	v_fmamk_f32 v58, v58, 0x3e38aa3b, v170
	v_mov_b32_e32 v57, v167
	ds_read2_b32 v[166:167], v157 offset0:88 offset1:89
	v_fmac_f32_e32 v171, 0x3e38aa3b, v59
	v_mov_b32_e32 v59, v171
	ds_read2_b32 v[170:171], v157 offset0:90 offset1:91
	s_waitcnt lgkmcnt(1)
	v_fmamk_f32 v60, v60, 0x3e38aa3b, v166
	v_fmac_f32_e32 v167, 0x3e38aa3b, v61
	v_mov_b32_e32 v61, v167
	v_max3_f32 v79, v169, v76, v78
	v_max3_f32 v169, v172, v77, v48
	v_max3_f32 v169, v169, v50, v52
	s_waitcnt lgkmcnt(0)
	v_fmamk_f32 v62, v62, 0x3e38aa3b, v170
	v_max3_f32 v169, v169, v54, v56
	v_max3_f32 v166, v169, v58, v60
	v_mov_b32_e32 v169, v62
	v_fmac_f32_e32 v171, 0x3e38aa3b, v63
	ds_read2_b32 v[62:63], v157 offset0:96 offset1:97
	v_mov_b32_e32 v208, v171
	v_max3_f32 v79, v79, v49, v51
	s_waitcnt lgkmcnt(0)
	v_fmamk_f32 v32, v32, 0x3e38aa3b, v62
	v_mov_b32_e32 v209, v32
	v_max3_f32 v32, v166, v169, v209
	ds_read2_b32 v[166:167], v157 offset0:98 offset1:99
	v_fmac_f32_e32 v63, 0x3e38aa3b, v33
	v_mov_b32_e32 v210, v63
	ds_read2_b32 v[62:63], v157 offset0:104 offset1:105
	s_waitcnt lgkmcnt(1)
	v_fmamk_f32 v33, v34, 0x3e38aa3b, v166
	v_fmac_f32_e32 v167, 0x3e38aa3b, v35
	s_waitcnt lgkmcnt(0)
	v_fmamk_f32 v35, v36, 0x3e38aa3b, v62
	v_mov_b32_e32 v34, v167
	ds_read2_b32 v[166:167], v157 offset0:106 offset1:107
	v_fmac_f32_e32 v63, 0x3e38aa3b, v37
	v_mov_b32_e32 v36, v63
	ds_read2_b32 v[62:63], v157 offset0:112 offset1:113
	s_waitcnt lgkmcnt(1)
	v_fmamk_f32 v37, v38, 0x3e38aa3b, v166
	v_fmac_f32_e32 v167, 0x3e38aa3b, v39
	s_waitcnt lgkmcnt(0)
	v_fmamk_f32 v39, v40, 0x3e38aa3b, v62
	v_mov_b32_e32 v38, v167
	ds_read2_b32 v[166:167], v157 offset0:114 offset1:115
	v_fmac_f32_e32 v63, 0x3e38aa3b, v41
	v_mov_b32_e32 v40, v63
	ds_read2_b32 v[62:63], v157 offset0:120 offset1:121
	s_waitcnt lgkmcnt(1)
	v_fmamk_f32 v41, v42, 0x3e38aa3b, v166
	v_fmac_f32_e32 v167, 0x3e38aa3b, v43
	s_waitcnt lgkmcnt(0)
	v_fmamk_f32 v43, v44, 0x3e38aa3b, v62
	v_mov_b32_e32 v42, v167
	ds_read2_b32 v[166:167], v157 offset0:122 offset1:123
	v_fmac_f32_e32 v63, 0x3e38aa3b, v45
	v_mov_b32_e32 v44, v63
	ds_read2_b32 v[62:63], v157 offset0:128 offset1:129
	s_waitcnt lgkmcnt(1)
	v_fmamk_f32 v45, v46, 0x3e38aa3b, v166
	v_fmac_f32_e32 v167, 0x3e38aa3b, v47
	s_waitcnt lgkmcnt(0)
	v_fmamk_f32 v16, v16, 0x3e38aa3b, v62
	v_mov_b32_e32 v46, v167
	ds_read2_b32 v[166:167], v157 offset0:130 offset1:131
	v_fmac_f32_e32 v63, 0x3e38aa3b, v17
	v_max3_f32 v79, v79, v53, v55
	v_max3_f32 v79, v79, v57, v59
	v_max3_f32 v79, v79, v61, v208
	s_waitcnt lgkmcnt(0)
	v_fmamk_f32 v18, v18, 0x3e38aa3b, v166
	v_fmac_f32_e32 v167, 0x3e38aa3b, v19
	v_max3_f32 v79, v79, v210, v34
	v_max3_f32 v79, v79, v36, v38
	v_mov_b32_e32 v17, v63
	ds_read2_b32 v[62:63], v157 offset0:136 offset1:137
	v_max3_f32 v79, v79, v40, v42
	v_max3_f32 v47, v79, v44, v46
	v_mov_b32_e32 v19, v167
	v_max3_f32 v79, v47, v17, v19
	ds_read2_b32 v[166:167], v157 offset0:138 offset1:139
	s_waitcnt lgkmcnt(1)
	v_fmamk_f32 v20, v20, 0x3e38aa3b, v62
	v_fmac_f32_e32 v63, 0x3e38aa3b, v21
	v_mov_b32_e32 v47, v63
	s_waitcnt lgkmcnt(0)
	v_fmamk_f32 v21, v22, 0x3e38aa3b, v166
	ds_read2_b32 v[62:63], v157 offset0:144 offset1:145
	v_mov_b32_e32 v211, v21
	v_fmac_f32_e32 v167, 0x3e38aa3b, v23
	v_mov_b32_e32 v23, v167
	ds_read2_b32 v[166:167], v157 offset0:146 offset1:147
	s_waitcnt lgkmcnt(1)
	v_fmamk_f32 v22, v24, 0x3e38aa3b, v62
	v_fmac_f32_e32 v63, 0x3e38aa3b, v25
	s_waitcnt lgkmcnt(0)
	v_fmamk_f32 v25, v26, 0x3e38aa3b, v166
	v_mov_b32_e32 v24, v63
	ds_read2_b32 v[62:63], v157 offset0:152 offset1:153
	v_fmac_f32_e32 v167, 0x3e38aa3b, v27
	v_max3_f32 v21, v79, v47, v23
	v_mov_b32_e32 v27, v167
	v_max3_f32 v79, v21, v24, v27
	s_waitcnt lgkmcnt(0)
	v_fmamk_f32 v21, v28, 0x3e38aa3b, v62
	v_fmac_f32_e32 v63, 0x3e38aa3b, v29
	ds_read2_b32 v[28:29], v157 offset0:154 offset1:155
	s_waitcnt lgkmcnt(0)
	v_fmamk_f32 v28, v30, 0x3e38aa3b, v28
	v_fmac_f32_e32 v29, 0x3e38aa3b, v31
	ds_read2_b32 v[30:31], v157 offset0:160 offset1:161
	v_max3_f32 v32, v32, v33, v35
	v_max3_f32 v32, v32, v37, v39
	s_waitcnt lgkmcnt(0)
	v_fmamk_f32 v0, v0, 0x3e38aa3b, v30
	v_max3_f32 v32, v32, v41, v43
	v_max3_f32 v32, v32, v45, v16
	v_max3_f32 v32, v32, v18, v20
	v_mov_b32_e32 v223, v0
	v_fmac_f32_e32 v31, 0x3e38aa3b, v1
	ds_read2_b32 v[0:1], v157 offset0:162 offset1:163
	v_max3_f32 v32, v32, v211, v22
	v_max3_f32 v32, v32, v25, v21
	v_max3_f32 v30, v32, v28, v223
	s_waitcnt lgkmcnt(0)
	v_fmamk_f32 v0, v2, 0x3e38aa3b, v0
	v_mov_b32_e32 v225, v0
	v_fmac_f32_e32 v1, 0x3e38aa3b, v3
	ds_read2_b32 v[2:3], v157 offset0:168 offset1:169
	v_mov_b32_e32 v227, v1
	s_waitcnt lgkmcnt(0)
	v_fmamk_f32 v0, v4, 0x3e38aa3b, v2
	v_mov_b32_e32 v228, v0
	ds_read2_b32 v[0:1], v157 offset0:170 offset1:171
	v_fmac_f32_e32 v3, 0x3e38aa3b, v5
	v_mov_b32_e32 v230, v3
	s_waitcnt lgkmcnt(0)
	v_fmamk_f32 v0, v6, 0x3e38aa3b, v0
	v_mov_b32_e32 v232, v0
	ds_read2_b32 v[2:3], v157 offset0:176 offset1:177
	v_fmac_f32_e32 v1, 0x3e38aa3b, v7
	v_mov_b32_e32 v233, v1
	s_waitcnt lgkmcnt(0)
	v_fmamk_f32 v0, v8, 0x3e38aa3b, v2
	v_mov_b32_e32 v231, v0
	ds_read2_b32 v[0:1], v157 offset0:178 offset1:179
	v_fmac_f32_e32 v3, 0x3e38aa3b, v9
	v_mov_b32_e32 v234, v3
	s_waitcnt lgkmcnt(0)
	v_fmamk_f32 v0, v10, 0x3e38aa3b, v0
	v_mov_b32_e32 v235, v0
	ds_read2_b32 v[2:3], v157 offset0:184 offset1:185
	v_fmac_f32_e32 v1, 0x3e38aa3b, v11
	v_mov_b32_e32 v236, v1
	s_waitcnt lgkmcnt(0)
	v_fmamk_f32 v0, v12, 0x3e38aa3b, v2
	v_max3_f32 v4, v30, v225, v228
	v_max3_f32 v4, v4, v232, v231
	v_mov_b32_e32 v237, v0
	v_max3_f32 v2, v4, v235, v237
	ds_read2_b32 v[0:1], v157 offset0:186 offset1:187
	v_fmac_f32_e32 v3, 0x3e38aa3b, v13
	v_mov_b32_e32 v240, v3
	s_waitcnt lgkmcnt(0)
	v_fmamk_f32 v0, v14, 0x3e38aa3b, v0
	v_mov_b32_e32 v26, v63
	v_mov_b32_e32 v224, v29
	v_mov_b32_e32 v239, v0
	v_max3_f32 v29, v79, v26, v224
	v_mov_b32_e32 v226, v31
	v_max3_f32 v29, v29, v226, v227
	v_fmac_f32_e32 v1, 0x3e38aa3b, v15
	v_max3_f32 v5, v29, v230, v233
	v_max3_f32 v5, v5, v234, v236
	v_mov_b32_e32 v241, v1
	v_max3_f32 v0, v5, v240, v241
	v_max3_f32 v0, v2, v239, v0
; #define LAS __attribute__((address_space(3)))
; #define MFMA32(a, b, c) __builtin_amdgcn_mfma_f32_32x32x16_bf16((a), (b), (c), 0, 0, 0)
; __device__ __forceinline__ s16x4 lds_tr(const LAS unsigned char* p) { return __builtin_bit_cast(s16x4, __builtin_amdgcn_ds_read_tr16_b64_v4i16((LAS v4i16_t*)p)); }
; __device__ __forceinline__ void attnA_unit(LAS unsigned char* lds, const Args& A, int unit) {
;     ...
;                 float mx = fmaxf(mxp[0], mxp[1]);
;                 mx = fmaxf(mx, __shfl_xor(mx, 32));
;                 float lsp[2] = {0.f, 0.f};
; #pragma unroll
;                 for (int kt = 0; kt < 5; ++kt)
; #pragma unroll
;                     for (int i = 0; i < 16; ++i) { const float p = __builtin_amdgcn_exp2f(S[kt][i] - mx); S[kt][i] = p; lsp[i & 1] += p; }
;                 float ls = lsp[0] + lsp[1];
;                 ls += __shfl_xor(ls, 32);
;                 f32x16 o0, o1;
; #pragma unroll
;                 for (int i = 0; i < 16; ++i) { o0[i] = 0.f; o1[i] = 0.f; }
;                 const LAS unsigned char* vr0 = vt_l + (rb + 4 * hh + ((lane & 15) >> 2)) * AST + 32 * ((lane >> 4) & 1) + 8 * (lane & 3);
; #pragma unroll
;                 for (int kt = 0; kt < 5; ++kt)
; #pragma unroll
;                     for (int ks = 0; ks < 2; ++ks) {
;                         const bf16x8 pf = pack_frag(S[kt], ks);
;                         const LAS unsigned char* vr = vr0 + (32 * kt + 16 * ks) * AST;
;                         const s16x4 a0 = lds_tr(vr), a1 = lds_tr(vr + 8 * AST), c0 = lds_tr(vr + 64), c1 = lds_tr(vr + 8 * AST + 64);
;                         o0 = MFMA32(__builtin_shufflevector(a0, a1, 0, 1, 2, 3, 4, 5, 6, 7), pf, o0);
;                         o1 = MFMA32(__builtin_shufflevector(c0, c1, 0, 1, 2, 3, 4, 5, 6, 7), pf, o1);
;                     }
.LmixA_join:
	v_and_b32_e32 v2, 64, v217
	v_xor_b32_e32 v1, 32, v217
	v_add_u32_e32 v2, 64, v2
	v_cmp_lt_i32_e32 vcc, v1, v2
	v_lshlrev_b32_e32 v32, v206, v164
	s_nop 0
	v_cndmask_b32_e32 v1, v217, v1, vcc
	v_lshlrev_b32_e32 v238, 2, v1
	ds_bpermute_b32 v1, v238, v0
	s_waitcnt lgkmcnt(0)
	v_max_f32_e32 v1, v1, v1
	v_max_f32_e32 v229, v0, v1
	v_sub_f32_e32 v10, v75, v229
	v_exp_f32_e32 v172, v10
	v_sub_f32_e32 v10, v76, v229
	v_exp_f32_e32 v173, v10
	v_sub_f32_e32 v10, v77, v229
	v_exp_f32_e32 v174, v10
	v_sub_f32_e32 v10, v78, v229
	v_exp_f32_e32 v175, v10
	v_sub_f32_e32 v10, v48, v229
	v_sub_f32_e32 v8, v72, v229
	v_exp_f32_e32 v72, v10
	v_sub_f32_e32 v10, v49, v229
	v_exp_f32_e32 v166, v8
	v_sub_f32_e32 v8, v73, v229
	v_exp_f32_e32 v73, v10
	v_sub_f32_e32 v10, v50, v229
	v_exp_f32_e32 v167, v8
	v_sub_f32_e32 v8, v74, v229
	v_exp_f32_e32 v74, v10
	v_sub_f32_e32 v10, v51, v229
	v_exp_f32_e32 v75, v10
	v_sub_f32_e32 v10, v52, v229
	v_exp_f32_e32 v76, v10
	v_sub_f32_e32 v10, v53, v229
	v_exp_f32_e32 v77, v10
	v_sub_f32_e32 v10, v54, v229
	v_exp_f32_e32 v78, v10
	v_sub_f32_e32 v10, v55, v229
	v_exp_f32_e32 v79, v10
	v_sub_f32_e32 v10, v56, v229
	v_exp_f32_e32 v62, v10
	v_sub_f32_e32 v10, v57, v229
	v_exp_f32_e32 v63, v10
	v_sub_f32_e32 v10, v58, v229
	v_sub_f32_e32 v2, v66, v229
	v_exp_f32_e32 v66, v10
	v_sub_f32_e32 v10, v59, v229
	v_sub_f32_e32 v0, v64, v229
	v_sub_f32_e32 v1, v65, v229
	v_sub_f32_e32 v3, v67, v229
	v_exp_f32_e32 v67, v10
	v_sub_f32_e32 v10, v60, v229
	v_exp_f32_e32 v0, v0
	v_exp_f32_e32 v1, v1
	v_sub_f32_e32 v4, v68, v229
	v_exp_f32_e32 v68, v10
	v_sub_f32_e32 v10, v61, v229
	v_exp_f32_e32 v2, v2
	v_exp_f32_e32 v3, v3
	v_sub_f32_e32 v5, v69, v229
	v_exp_f32_e32 v69, v10
	v_sub_f32_e32 v10, v169, v229
	v_exp_f32_e32 v4, v4
	v_exp_f32_e32 v5, v5
	v_sub_f32_e32 v6, v70, v229
	v_sub_f32_e32 v7, v71, v229
	v_exp_f32_e32 v70, v10
	v_sub_f32_e32 v10, v208, v229
	v_exp_f32_e32 v6, v6
	v_exp_f32_e32 v7, v7
	v_exp_f32_e32 v170, v8
	v_sub_f32_e32 v8, v168, v229
	v_exp_f32_e32 v71, v10
	v_sub_f32_e32 v10, v209, v229
	v_exp_f32_e32 v171, v8
	v_pk_add_f32 v[8:9], v[0:1], 0 op_sel_hi:[1,0]
	v_exp_f32_e32 v54, v10
	v_sub_f32_e32 v10, v210, v229
	v_pk_add_f32 v[8:9], v[2:3], v[8:9]
	v_exp_f32_e32 v55, v10
	v_sub_f32_e32 v10, v33, v229
	v_pk_add_f32 v[8:9], v[4:5], v[8:9]
	v_exp_f32_e32 v58, v10
	v_sub_f32_e32 v10, v34, v229
	v_pk_add_f32 v[8:9], v[6:7], v[8:9]
	v_exp_f32_e32 v59, v10
	v_sub_f32_e32 v10, v35, v229
	v_pk_add_f32 v[8:9], v[166:167], v[8:9]
	v_exp_f32_e32 v60, v10
	v_sub_f32_e32 v10, v36, v229
	v_pk_add_f32 v[8:9], v[170:171], v[8:9]
	v_exp_f32_e32 v61, v10
	v_sub_f32_e32 v10, v37, v229
	v_pk_add_f32 v[8:9], v[172:173], v[8:9]
	v_exp_f32_e32 v64, v10
	v_sub_f32_e32 v10, v38, v229
	v_pk_add_f32 v[8:9], v[174:175], v[8:9]
	v_exp_f32_e32 v65, v10
	v_sub_f32_e32 v10, v39, v229
	v_pk_add_f32 v[8:9], v[72:73], v[8:9]
	v_exp_f32_e32 v48, v10
	v_sub_f32_e32 v10, v40, v229
	v_pk_add_f32 v[8:9], v[74:75], v[8:9]
	v_exp_f32_e32 v49, v10
	v_sub_f32_e32 v10, v41, v229
	v_pk_add_f32 v[8:9], v[76:77], v[8:9]
	v_exp_f32_e32 v50, v10
	v_sub_f32_e32 v10, v42, v229
	v_pk_add_f32 v[8:9], v[78:79], v[8:9]
	v_exp_f32_e32 v51, v10
	v_sub_f32_e32 v10, v43, v229
	v_pk_add_f32 v[8:9], v[62:63], v[8:9]
	v_exp_f32_e32 v52, v10
	v_sub_f32_e32 v10, v44, v229
	v_pk_add_f32 v[8:9], v[66:67], v[8:9]
	v_exp_f32_e32 v53, v10
	v_sub_f32_e32 v10, v45, v229
	v_pk_add_f32 v[8:9], v[68:69], v[8:9]
	v_exp_f32_e32 v56, v10
	v_sub_f32_e32 v10, v46, v229
	v_pk_add_f32 v[8:9], v[70:71], v[8:9]
	v_exp_f32_e32 v57, v10
	v_sub_f32_e32 v10, v16, v229
	v_pk_add_f32 v[8:9], v[54:55], v[8:9]
	v_exp_f32_e32 v38, v10
	v_sub_f32_e32 v10, v17, v229
	v_exp_f32_e32 v39, v10
	v_sub_f32_e32 v10, v18, v229
	v_pk_add_f32 v[8:9], v[58:59], v[8:9]
	v_exp_f32_e32 v40, v10
	v_sub_f32_e32 v10, v19, v229
	v_pk_add_f32 v[8:9], v[60:61], v[8:9]
	v_exp_f32_e32 v41, v10
	v_sub_f32_e32 v10, v20, v229
	v_pk_add_f32 v[8:9], v[64:65], v[8:9]
	v_exp_f32_e32 v42, v10
	v_sub_f32_e32 v10, v47, v229
	v_pk_add_f32 v[8:9], v[48:49], v[8:9]
	v_exp_f32_e32 v43, v10
	v_sub_f32_e32 v10, v211, v229
	v_pk_add_f32 v[8:9], v[50:51], v[8:9]
	v_exp_f32_e32 v44, v10
	v_sub_f32_e32 v10, v23, v229
	v_pk_add_f32 v[8:9], v[52:53], v[8:9]
	v_exp_f32_e32 v45, v10
	v_pk_add_f32 v[8:9], v[56:57], v[8:9]
	v_sub_f32_e32 v12, v27, v229
	v_pk_add_f32 v[8:9], v[38:39], v[8:9]
	v_cvt_pk_bf16_f32 v16, v0, v1
	v_pk_add_f32 v[8:9], v[40:41], v[8:9]
	v_cvt_pk_bf16_f32 v17, v2, v3
	v_pk_add_f32 v[8:9], v[42:43], v[8:9]
	v_cvt_pk_bf16_f32 v18, v4, v5
	v_pk_add_f32 v[46:47], v[44:45], v[8:9]
	v_sub_f32_e32 v8, v22, v229
	v_exp_f32_e32 v34, v8
	v_sub_f32_e32 v8, v24, v229
	v_exp_f32_e32 v35, v8
	v_sub_f32_e32 v8, v25, v229
	v_exp_f32_e32 v36, v8
	v_add_u32_e32 v8, v180, v163
	v_mad_u64_u32 v[246:247], s[22:23], v8, s88, v[152:153]
	ds_read_b64_tr_b16 v[8:9], v246 offset:59392
	ds_read_b64_tr_b16 v[10:11], v246 offset:60544
	v_cvt_pk_bf16_f32 v19, v6, v7
	v_exp_f32_e32 v37, v12
	v_sub_f32_e32 v24, v21, v229
	ds_read_b64_tr_b16 v[20:21], v246 offset:59456
	ds_read_b64_tr_b16 v[22:23], v246 offset:60608
	s_waitcnt lgkmcnt(2)
	v_mfma_f32_32x32x16_bf16 v[0:15], v[8:11], v[16:19], 0
	v_exp_f32_e32 v164, v24
	v_sub_f32_e32 v24, v26, v229
	ds_read_b64_tr_b16 v[208:209], v246 offset:61696
	ds_read_b64_tr_b16 v[210:211], v246 offset:62848
	v_exp_f32_e32 v165, v24
	v_sub_f32_e32 v24, v28, v229
	v_exp_f32_e32 v168, v24
	v_cvt_pk_bf16_f32 v242, v166, v167
	s_waitcnt lgkmcnt(2)
; #define LAS __attribute__((address_space(3)))
; #define MFMA32(a, b, c) __builtin_amdgcn_mfma_f32_32x32x16_bf16((a), (b), (c), 0, 0, 0)
; __device__ __forceinline__ s16x4 lds_tr(const LAS unsigned char* p) { return __builtin_bit_cast(s16x4, __builtin_amdgcn_ds_read_tr16_b64_v4i16((LAS v4i16_t*)p)); }
; __device__ __forceinline__ void attnA_unit(LAS unsigned char* lds, const Args& A, int unit) {
;     ...
;                 const LAS unsigned char* vr0 = vt_l + (rb + 4 * hh + ((lane & 15) >> 2)) * AST + 32 * ((lane >> 4) & 1) + 8 * (lane & 3);
; #pragma unroll
;                 for (int kt = 0; kt < 5; ++kt)
; #pragma unroll
;                     for (int ks = 0; ks < 2; ++ks) {
;                         const bf16x8 pf = pack_frag(S[kt], ks);
;                         const LAS unsigned char* vr = vr0 + (32 * kt + 16 * ks) * AST;
;                         const s16x4 a0 = lds_tr(vr), a1 = lds_tr(vr + 8 * AST), c0 = lds_tr(vr + 64), c1 = lds_tr(vr + 8 * AST + 64);
;                         o0 = MFMA32(__builtin_shufflevector(a0, a1, 0, 1, 2, 3, 4, 5, 6, 7), pf, o0);
;                         o1 = MFMA32(__builtin_shufflevector(c0, c1, 0, 1, 2, 3, 4, 5, 6, 7), pf, o1);
;                     }
	v_mfma_f32_32x32x16_bf16 v[16:31], v[20:23], v[16:19], 0
	v_cvt_pk_bf16_f32 v243, v170, v171
	v_cvt_pk_bf16_f32 v244, v172, v173
	v_cvt_pk_bf16_f32 v245, v174, v175
	ds_read_b64_tr_b16 v[170:171], v246 offset:61760
	ds_read_b64_tr_b16 v[172:173], v246 offset:62912
	v_add_u32_e32 v163, 0xe800, v246
	v_cvt_pk_bf16_f32 v48, v48, v49
	v_cvt_pk_bf16_f32 v49, v50, v51
	s_waitcnt lgkmcnt(2)
	v_mfma_f32_32x32x16_bf16 v[0:15], v[208:211], v[242:245], v[0:15]
	ds_read_b64_tr_b16 v[208:209], v246 offset:64000
	ds_read_b64_tr_b16 v[210:211], v246 offset:65152
	v_cvt_pk_bf16_f32 v50, v52, v53
	v_cvt_pk_bf16_f32 v51, v56, v57
	v_sub_f32_e32 v33, v224, v229
	v_exp_f32_e32 v169, v33
	v_sub_f32_e32 v33, v223, v229
	v_cvt_pk_bf16_f32 v38, v38, v39
	s_waitcnt lgkmcnt(2)
	v_mfma_f32_32x32x16_bf16 v[16:31], v[170:173], v[242:245], v[16:31]
	v_cvt_pk_bf16_f32 v170, v72, v73
	v_cvt_pk_bf16_f32 v171, v74, v75
	v_cvt_pk_bf16_f32 v172, v76, v77
	v_cvt_pk_bf16_f32 v173, v78, v79
	ds_read_b64_tr_b16 v[74:75], v246 offset:64064
	ds_read_b64_tr_b16 v[76:77], v246 offset:65216
	v_cvt_pk_bf16_f32 v78, v68, v69
	v_cvt_pk_bf16_f32 v79, v70, v71
	s_waitcnt lgkmcnt(2)
	v_mfma_f32_32x32x16_bf16 v[0:15], v[208:211], v[170:173], v[0:15]
	ds_read_b64_tr_b16 v[208:209], v163 offset:6912
	ds_read_b64_tr_b16 v[210:211], v163 offset:8064
	v_cvt_pk_bf16_f32 v39, v40, v41
	v_cvt_pk_bf16_f32 v40, v42, v43
	v_cvt_pk_bf16_f32 v41, v44, v45
	v_exp_f32_e32 v166, v33
	v_sub_f32_e32 v33, v226, v229
	v_exp_f32_e32 v167, v33
	s_waitcnt lgkmcnt(2)
	v_mfma_f32_32x32x16_bf16 v[16:31], v[74:77], v[170:173], v[16:31]
	v_cvt_pk_bf16_f32 v76, v62, v63
	v_cvt_pk_bf16_f32 v77, v66, v67
	ds_read_b64_tr_b16 v[66:67], v163 offset:6976
	ds_read_b64_tr_b16 v[68:69], v163 offset:8128
	ds_read_b64_tr_b16 v[170:171], v163 offset:9216
	ds_read_b64_tr_b16 v[172:173], v163 offset:10368
	v_sub_f32_e32 v33, v225, v229
	v_exp_f32_e32 v72, v33
	v_sub_f32_e32 v33, v227, v229
	s_waitcnt lgkmcnt(4)
	v_mfma_f32_32x32x16_bf16 v[0:15], v[208:211], v[76:79], v[0:15]
	v_exp_f32_e32 v73, v33
	v_sub_f32_e32 v33, v228, v229
	v_exp_f32_e32 v74, v33
	v_sub_f32_e32 v33, v230, v229
	v_exp_f32_e32 v75, v33
	v_sub_f32_e32 v33, v232, v229
	v_exp_f32_e32 v62, v33
	s_waitcnt lgkmcnt(2)
	v_mfma_f32_32x32x16_bf16 v[16:31], v[66:69], v[76:79], v[16:31]
	v_cvt_pk_bf16_f32 v66, v54, v55
	v_cvt_pk_bf16_f32 v67, v58, v59
	v_cvt_pk_bf16_f32 v68, v60, v61
	v_cvt_pk_bf16_f32 v69, v64, v65
	ds_read_b64_tr_b16 v[58:59], v163 offset:9280
	ds_read_b64_tr_b16 v[60:61], v163 offset:10432
	ds_read_b64_tr_b16 v[76:77], v163 offset:11520
	ds_read_b64_tr_b16 v[78:79], v163 offset:12672
	v_sub_f32_e32 v33, v233, v229
	s_waitcnt lgkmcnt(4)
	v_mfma_f32_32x32x16_bf16 v[0:15], v[170:173], v[66:69], v[0:15]
	v_exp_f32_e32 v63, v33
	v_sub_f32_e32 v33, v231, v229
	v_exp_f32_e32 v54, v33
	v_sub_f32_e32 v33, v234, v229
	v_exp_f32_e32 v55, v33
	v_sub_f32_e32 v33, v235, v229
	s_waitcnt lgkmcnt(2)
	v_mfma_f32_32x32x16_bf16 v[16:31], v[58:61], v[66:69], v[16:31]
	ds_read_b64_tr_b16 v[56:57], v163 offset:11584
	ds_read_b64_tr_b16 v[58:59], v163 offset:12736
	ds_read_b64_tr_b16 v[64:65], v163 offset:13824
	ds_read_b64_tr_b16 v[66:67], v163 offset:14976
	ds_read_b64_tr_b16 v[42:43], v163 offset:13888
	ds_read_b64_tr_b16 v[44:45], v163 offset:15040
	v_exp_f32_e32 v60, v33
	v_sub_f32_e32 v33, v236, v229
	v_exp_f32_e32 v61, v33
	v_sub_f32_e32 v33, v237, v229
	s_waitcnt lgkmcnt(6)
	v_mfma_f32_32x32x16_bf16 v[0:15], v[76:79], v[48:51], v[0:15]
	v_exp_f32_e32 v52, v33
	v_sub_f32_e32 v33, v240, v229
	v_exp_f32_e32 v53, v33
	v_sub_f32_e32 v33, v239, v229
	s_waitcnt lgkmcnt(4)
	v_mfma_f32_32x32x16_bf16 v[16:31], v[56:59], v[48:51], v[16:31]
	v_add_f32_e64 v56, v34, v46
	v_add_f32_e64 v57, v35, v47
	ds_read_b64_tr_b16 v[46:47], v163 offset:16128
	ds_read_b64_tr_b16 v[48:49], v163 offset:17280
	v_cvt_pk_bf16_f32 v34, v34, v35
	v_cvt_pk_bf16_f32 v35, v36, v37
	v_exp_f32_e32 v50, v33
	v_sub_f32_e32 v33, v241, v229
	v_exp_f32_e32 v51, v33
	s_waitcnt lgkmcnt(4)
	v_mfma_f32_32x32x16_bf16 v[0:15], v[64:67], v[38:41], v[0:15]
	s_waitcnt lgkmcnt(2)
	v_mfma_f32_32x32x16_bf16 v[16:31], v[42:45], v[38:41], v[16:31]
	v_add_f32_e64 v42, v36, v56
	v_add_f32_e64 v43, v37, v57
	v_cvt_pk_bf16_f32 v36, v164, v165
	v_cvt_pk_bf16_f32 v37, v168, v169
	v_add_f32_e64 v42, v164, v42
	v_add_f32_e64 v43, v165, v43
	ds_read_b64_tr_b16 v[38:39], v163 offset:16192
	ds_read_b64_tr_b16 v[40:41], v163 offset:17344
	v_pk_add_f32 v[42:43], v[168:169], v[42:43]
	s_waitcnt lgkmcnt(2)
; #define LAS __attribute__((address_space(3)))
; #define MFMA32(a, b, c) __builtin_amdgcn_mfma_f32_32x32x16_bf16((a), (b), (c), 0, 0, 0)
; __device__ __forceinline__ unsigned cvtpk(float lo, float hi) { f32x2_t v = {lo, hi}; bf16x2_t b = __builtin_convertvector(v, bf16x2_t); return __builtin_bit_cast(unsigned, b); }
; __device__ __forceinline__ s16x4 lds_tr(const LAS unsigned char* p) { return __builtin_bit_cast(s16x4, __builtin_amdgcn_ds_read_tr16_b64_v4i16((LAS v4i16_t*)p)); }
; __device__ __forceinline__ void attnA_unit(LAS unsigned char* lds, const Args& A, int unit) {
;     ...
;                 float ls = lsp[0] + lsp[1];
;                 ls += __shfl_xor(ls, 32);
;                 f32x16 o0, o1;
; #pragma unroll
;                 for (int i = 0; i < 16; ++i) { o0[i] = 0.f; o1[i] = 0.f; }
;                 const LAS unsigned char* vr0 = vt_l + (rb + 4 * hh + ((lane & 15) >> 2)) * AST + 32 * ((lane >> 4) & 1) + 8 * (lane & 3);
; #pragma unroll
;                 for (int kt = 0; kt < 5; ++kt)
; #pragma unroll
;                     for (int ks = 0; ks < 2; ++ks) {
;                         const bf16x8 pf = pack_frag(S[kt], ks);
;                         const LAS unsigned char* vr = vr0 + (32 * kt + 16 * ks) * AST;
;                         const s16x4 a0 = lds_tr(vr), a1 = lds_tr(vr + 8 * AST), c0 = lds_tr(vr + 64), c1 = lds_tr(vr + 8 * AST + 64);
;                         o0 = MFMA32(__builtin_shufflevector(a0, a1, 0, 1, 2, 3, 4, 5, 6, 7), pf, o0);
;                         o1 = MFMA32(__builtin_shufflevector(c0, c1, 0, 1, 2, 3, 4, 5, 6, 7), pf, o1);
;                     }
;                 const float inv = 1.0f / ls;
;                 bf16* orow = Qrow + 4 * hh;
; #pragma unroll
;                 for (int g4 = 0; g4 < 4; ++g4) {
;                     u32x2 w; w.x = cvtpk(o0[4 * g4] * inv, o0[4 * g4 + 1] * inv); w.y = cvtpk(o0[4 * g4 + 2] * inv, o0[4 * g4 + 3] * inv); *(u32x2*)(orow + 8 * g4) = w;
;                     u32x2 z; z.x = cvtpk(o1[4 * g4] * inv, o1[4 * g4 + 1] * inv); z.y = cvtpk(o1[4 * g4 + 2] * inv, o1[4 * g4 + 3] * inv); *(u32x2*)(orow + 32 + 8 * g4) = z;
;                 }
;                 if (hh == 0) LSE[(size_t)((g * 4 + b) * 8 + h) * 8192 + pbase + i0 + ql] = mx + __builtin_amdgcn_logf(ls);
	v_mfma_f32_32x32x16_bf16 v[0:15], v[46:49], v[34:37], v[0:15]
	v_add_f32_e64 v42, v166, v42
	v_add_f32_e64 v43, v167, v43
	v_add_f32_e64 v42, v72, v42
	v_add_f32_e64 v43, v73, v43
	v_add_f32_e64 v46, v74, v42
	v_add_f32_e64 v47, v75, v43
	ds_read_b64_tr_b16 v[42:43], v163 offset:18432
	ds_read_b64_tr_b16 v[44:45], v163 offset:19584
	v_pk_add_f32 v[46:47], v[62:63], v[46:47]
	s_waitcnt lgkmcnt(2)
	v_mfma_f32_32x32x16_bf16 v[16:31], v[38:41], v[34:37], v[16:31]
	v_cvt_pk_bf16_f32 v34, v166, v167
	v_cvt_pk_bf16_f32 v35, v72, v73
	v_cvt_pk_bf16_f32 v36, v74, v75
	v_cvt_pk_bf16_f32 v37, v62, v63
	ds_read_b64_tr_b16 v[38:39], v163 offset:18496
	ds_read_b64_tr_b16 v[40:41], v163 offset:19648
	s_waitcnt lgkmcnt(2)
	v_mfma_f32_32x32x16_bf16 v[0:15], v[42:45], v[34:37], v[0:15]
	v_add_f32_e64 v42, v54, v46
	v_add_f32_e64 v43, v55, v47
	v_add_f32_e64 v42, v60, v42
	v_add_f32_e64 v43, v61, v43
	v_add_f32_e64 v42, v52, v42
	v_add_f32_e64 v43, v53, v43
	v_pk_add_f32 v[42:43], v[50:51], v[42:43]
	s_waitcnt lgkmcnt(0)
	v_mfma_f32_32x32x16_bf16 v[16:31], v[38:41], v[34:37], v[16:31]
	v_add_f32_e32 v33, v42, v43
	ds_bpermute_b32 v34, v238, v33
	ds_read_b64_tr_b16 v[42:43], v163 offset:20736
	ds_read_b64_tr_b16 v[44:45], v163 offset:21888
	ds_read_b64_tr_b16 v[46:47], v163 offset:20800
	ds_read_b64_tr_b16 v[48:49], v163 offset:21952
	v_cvt_pk_bf16_f32 v36, v54, v55
	v_cvt_pk_bf16_f32 v37, v60, v61
	s_waitcnt lgkmcnt(4)
	v_add_f32_e32 v34, v33, v34
	v_div_scale_f32 v33, s[22:23], v34, v34, 1.0
	v_rcp_f32_e32 v35, v33
	v_cvt_pk_bf16_f32 v38, v52, v53
	v_cvt_pk_bf16_f32 v39, v50, v51
	v_add3_u32 v40, v162, v144, v32
	v_ashrrev_i32_e32 v41, 31, v40
	s_waitcnt lgkmcnt(2)
	v_mfma_f32_32x32x16_bf16 v[0:15], v[42:45], v[36:39], v[0:15]
	v_lshlrev_b64 v[40:41], 7, v[40:41]
	s_waitcnt lgkmcnt(0)
	v_mfma_f32_32x32x16_bf16 v[16:31], v[46:49], v[36:39], v[16:31]
	v_fma_f32 v36, -v33, v35, 1.0
	v_fmac_f32_e32 v35, v36, v35
	v_div_scale_f32 v36, vcc, 1.0, v34, 1.0
	v_mul_f32_e32 v37, v36, v35
	v_fma_f32 v38, -v33, v37, v36
	v_fmac_f32_e32 v37, v38, v35
	v_fma_f32 v33, -v33, v37, v36
	v_div_fmas_f32 v33, v33, v35, v37
	v_div_fixup_f32 v36, v33, v34, 1.0
	v_pk_mul_f32 v[0:1], v[36:37], v[0:1] op_sel_hi:[0,1]
	v_pk_mul_f32 v[2:3], v[36:37], v[2:3] op_sel_hi:[0,1]
	v_lshl_add_u64 v[38:39], v[160:161], 0, v[40:41]
	v_cvt_pk_bf16_f32 v0, v0, v1
	v_cvt_pk_bf16_f32 v1, v2, v3
	global_store_dwordx2 v[38:39], v[0:1], off
	v_pk_mul_f32 v[0:1], v[36:37], v[16:17] op_sel_hi:[0,1]
	v_pk_mul_f32 v[2:3], v[36:37], v[18:19] op_sel_hi:[0,1]
	v_cvt_pk_bf16_f32 v0, v0, v1
	v_cvt_pk_bf16_f32 v1, v2, v3
	global_store_dwordx2 v[38:39], v[0:1], off offset:64
	v_pk_mul_f32 v[0:1], v[36:37], v[4:5] op_sel_hi:[0,1]
	v_pk_mul_f32 v[2:3], v[36:37], v[6:7] op_sel_hi:[0,1]
	v_cvt_pk_bf16_f32 v0, v0, v1
	v_cvt_pk_bf16_f32 v1, v2, v3
	global_store_dwordx2 v[38:39], v[0:1], off offset:16
	v_pk_mul_f32 v[0:1], v[36:37], v[20:21] op_sel_hi:[0,1]
	v_pk_mul_f32 v[2:3], v[36:37], v[22:23] op_sel_hi:[0,1]
	v_cvt_pk_bf16_f32 v0, v0, v1
	v_cvt_pk_bf16_f32 v1, v2, v3
	global_store_dwordx2 v[38:39], v[0:1], off offset:80
	v_pk_mul_f32 v[0:1], v[36:37], v[8:9] op_sel_hi:[0,1]
	v_pk_mul_f32 v[2:3], v[36:37], v[10:11] op_sel_hi:[0,1]
	v_cvt_pk_bf16_f32 v0, v0, v1
	v_cvt_pk_bf16_f32 v1, v2, v3
	global_store_dwordx2 v[38:39], v[0:1], off offset:32
	v_pk_mul_f32 v[0:1], v[36:37], v[24:25] op_sel_hi:[0,1]
	v_pk_mul_f32 v[2:3], v[36:37], v[26:27] op_sel_hi:[0,1]
	v_cvt_pk_bf16_f32 v0, v0, v1
	v_cvt_pk_bf16_f32 v1, v2, v3
	global_store_dwordx2 v[38:39], v[0:1], off offset:96
	v_pk_mul_f32 v[0:1], v[36:37], v[12:13] op_sel_hi:[0,1]
	v_pk_mul_f32 v[2:3], v[36:37], v[14:15] op_sel_hi:[0,1]
	v_cvt_pk_bf16_f32 v0, v0, v1
	v_cvt_pk_bf16_f32 v1, v2, v3
	global_store_dwordx2 v[38:39], v[0:1], off offset:48
	v_pk_mul_f32 v[0:1], v[36:37], v[28:29] op_sel_hi:[0,1]
	v_pk_mul_f32 v[2:3], v[36:37], v[30:31] op_sel_hi:[0,1]
	v_cvt_pk_bf16_f32 v0, v0, v1
	v_cvt_pk_bf16_f32 v1, v2, v3
	global_store_dwordx2 v[38:39], v[0:1], off offset:112
	s_and_saveexec_b64 s[22:23], s[6:7]
	s_cbranch_execz .LBB0_303
	v_log_f32_e32 v2, v34
	v_ashrrev_i32_e32 v33, 31, v32
	v_lshl_add_u64 v[0:1], v[32:33], 2, s[80:81]
	v_ashrrev_i32_e32 v163, 31, v162
	v_lshl_add_u64 v[0:1], v[162:163], 2, v[0:1]
	v_lshl_add_u64 v[0:1], v[0:1], 0, v[184:185]
	v_add_f32_e32 v2, v229, v2
	global_store_dword v[0:1], v2, off

; __device__ __forceinline__ unsigned cvtpk(float lo, float hi) { f32x2_t v = {lo, hi}; bf16x2_t b = __builtin_convertvector(v, bf16x2_t); return __builtin_bit_cast(unsigned, b); }
; __device__ __forceinline__ int tid_fresh() { int t = threadIdx.x; asm volatile("" : "+v"(t)); return t; }
; __device__ __forceinline__ float bflo(unsigned u) { return __uint_as_float(u << 16); }
; __device__ __forceinline__ float bfhi(unsigned u) { return __uint_as_float(u & 0xffff0000u); }
; #define WRITE_TILE(bufp) do { LAS unsigned char* _k = (bufp); LAS unsigned char* _v = (bufp) + 64 * KST; \
;         *(LAS u32x4*)(_k + key * KST + ch * 16) = kreg; \
;         *(LAS u32x4*)(_v + key * VST + ch * 16) = vreg; } while (0)
; __device__ __forceinline__ void attnB_unit(LAS unsigned char* lds, const Args& A, int unit, const float* kng, bool do_store = true) {
;     const int tid = tid_fresh(), wave = tid >> 6, lane = tid & 63, ql = lane & 31, hh = lane >> 5;
;     const int qblk = unit & 31, hq = (unit >> 5) & 7, b = unit >> 8, kvh = hq >> 2;
;     const bf16* Qp = (const bf16*)(A.ws + WS_QB) + ((size_t)((b * 8 + hq) * 8192 + qblk * 256 + wave * 32 + ql) * 64);
;     bf16x8 qf[4];
; #pragma unroll
;     for (int s = 0; s < 4; ++s) { const u32x4 qw = *(const u32x4*)(Qp + 16 * s + 8 * hh);
;         u32x4 qs; qs.x = cvtpk(bflo(qw.x) * QK_C, bfhi(qw.x) * QK_C); qs.y = cvtpk(bflo(qw.y) * QK_C, bfhi(qw.y) * QK_C); qs.z = cvtpk(bflo(qw.z) * QK_C, bfhi(qw.z) * QK_C); qs.w = cvtpk(bflo(qw.w) * QK_C, bfhi(qw.w) * QK_C);
;         qf[s] = __builtin_bit_cast(bf16x8, qs); }
;     const int key = tid >> 3, ch = tid & 7;
;     const bf16* Kg = (const bf16*)(A.ws + WS_KB) + ((size_t)((b * 2 + kvh) * 8192 + key) * 64 + ch * 8);
;     const bf16* Vg = (const bf16*)(A.ws + WS_VB) + ((size_t)((b * 2 + kvh) * 8192 + key) * 64 + ch * 8);
;     f32x16 o0, o1;
; #pragma unroll
;     for (int i = 0; i < 16; ++i) { o0[i] = 0.f; o1[i] = 0.f; }
;     float m_used = -1e30f, l = 0.f; float lp[4] = {0.f, 0.f, 0.f, 0.f};
;     u32x4 kreg = *(const u32x4*)Kg, vreg = *(const u32x4*)Vg;
;     u32x4 kq1 = *(const u32x4*)(Kg + (size_t)64 * 64), vq1 = *(const u32x4*)(Vg + (size_t)64 * 64), kq0 = *(const u32x4*)(Kg + (size_t)2 * 64 * 64), vq0 = *(const u32x4*)(Vg + (size_t)2 * 64 * 64);
;     ...
;     __syncthreads();
;     WRITE_TILE(lds);
;     kreg = kq1; vreg = vq1;
;     WRITE_TILE(lds + BUF_B);
;     __syncthreads();
.LBB0_314:
	s_bfe_u32 s8, s4, 0x30005
	s_ashr_i32 s9, s4, 8
	s_lshl_b32 s5, s9, 16
	s_lshl_b32 s6, s8, 13
	s_lshl_b32 s7, s4, 8
	v_mov_b32_e32 v32, v212
	s_and_b32 s10, s7, 0x1f00
	s_or_b32 s5, s5, s6
	s_or_b32 s5, s5, s10
	v_and_b32_e32 v210, 31, v32
	v_ashrrev_i32_e32 v0, 1, v32
	v_and_b32_e32 v211, 0xffffffe0, v0
	v_or_b32_e32 v0, s5, v210
	v_add_u32_e32 v0, v0, v211
	v_ashrrev_i32_e32 v1, 31, v0
	v_readlane_b32 s6, v254, 51
	v_bfe_u32 v33, v32, 5, 1
	v_lshlrev_b64 v[0:1], 7, v[0:1]
	v_readlane_b32 s7, v254, 52
	v_lshlrev_b32_e32 v184, 4, v33
	s_lshl_b32 s4, s4, 6
	v_lshl_add_u64 v[0:1], s[6:7], 0, v[0:1]
	v_lshl_add_u64 v[4:5], v[0:1], 0, v[184:185]
	global_load_dwordx4 v[20:23], v[4:5], off
	global_load_dwordx4 v[24:27], v[4:5], off offset:32
	global_load_dwordx4 v[28:31], v[4:5], off offset:64
	global_load_dwordx4 v[36:39], v[4:5], off offset:96
	s_lshl_b32 s5, s9, 14
	s_and_b32 s4, s4, 0x2000
	v_ashrrev_i32_e32 v34, 3, v32
	s_or_b32 s4, s4, s5
	v_mul_lo_u32 v224, v34, s88
	v_mul_u32_u24_e32 v225, 0x90, v210
	v_add3_u32 v44, 0, v225, v184
	v_and_b32_e32 v35, 63, v32
	v_lshlrev_b32_e32 v35, 2, v35
	v_mov_b32_e32 v172, 0
	v_readlane_b32 s6, v255, 48
	v_readlane_b32 s7, v255, 49
	v_lshlrev_b32_e32 v2, 4, v32
	v_and_b32_e32 v223, 0x70, v2
	v_add_u32_e32 v0, s4, v34
	v_ashrrev_i32_e32 v1, 31, v0
	v_lshlrev_b64 v[0:1], 7, v[0:1]
	v_readlane_b32 s4, v254, 53
	v_or_b32_e32 v0, v0, v223
	v_readlane_b32 s5, v254, 54
	global_load_dword v35, v35, s[6:7]
	s_nop 1
	v_lshl_add_u64 v[168:169], s[4:5], 0, v[0:1]
	v_readlane_b32 s4, v254, 8
	v_readlane_b32 s5, v254, 9
	s_nop 1
	v_lshl_add_u64 v[170:171], s[4:5], 0, v[0:1]
	s_movk_i32 s4, 0x2000
	v_add_co_u32_e32 v8, vcc, s4, v168
	global_load_dwordx4 v[0:3], v[168:169], off
	global_load_dwordx4 v[4:7], v[170:171], off
	v_addc_co_u32_e32 v9, vcc, 0, v169, vcc
	v_add_co_u32_e32 v12, vcc, s4, v170
	global_load_dwordx4 v[8:11], v[8:9], off
	s_nop 0
	v_addc_co_u32_e32 v13, vcc, 0, v171, vcc
	global_load_dwordx4 v[12:15], v[12:13], off
	s_movk_i32 s4, 0x4000
	v_add_co_u32_e32 v16, vcc, s4, v168
	s_nop 1
	v_addc_co_u32_e32 v17, vcc, 0, v169, vcc
	global_load_dwordx4 v[144:147], v[16:17], off
	v_add_co_u32_e32 v16, vcc, s4, v170
	s_movk_i32 s4, 0xffd0
	s_nop 0
	v_addc_co_u32_e32 v17, vcc, 0, v171, vcc
	global_load_dwordx4 v[148:151], v[16:17], off
	s_waitcnt vmcnt(6)
	v_lshlrev_b32_e32 v40, 16, v20
	v_and_b32_e32 v41, 0xffff0000, v20
	v_pk_mul_f32 v[40:41], v[40:41], s[92:93] op_sel_hi:[1,0]
	v_cvt_pk_bf16_f32 v128, v40, v41
	v_lshlrev_b32_e32 v42, 16, v21
	v_and_b32_e32 v43, 0xffff0000, v21
	v_pk_mul_f32 v[42:43], v[42:43], s[92:93] op_sel_hi:[1,0]
	v_cvt_pk_bf16_f32 v129, v42, v43
	v_lshlrev_b32_e32 v40, 16, v22
	v_and_b32_e32 v41, 0xffff0000, v22
	v_pk_mul_f32 v[40:41], v[40:41], s[92:93] op_sel_hi:[1,0]
	v_cvt_pk_bf16_f32 v130, v40, v41
	v_lshlrev_b32_e32 v42, 16, v23
	v_and_b32_e32 v43, 0xffff0000, v23
	v_pk_mul_f32 v[42:43], v[42:43], s[92:93] op_sel_hi:[1,0]
	v_cvt_pk_bf16_f32 v131, v42, v43
	v_lshlrev_b32_e32 v40, 16, v24
	v_and_b32_e32 v41, 0xffff0000, v24
	v_pk_mul_f32 v[40:41], v[40:41], s[92:93] op_sel_hi:[1,0]
	v_cvt_pk_bf16_f32 v132, v40, v41
	v_lshlrev_b32_e32 v42, 16, v25
	v_and_b32_e32 v43, 0xffff0000, v25
	v_pk_mul_f32 v[42:43], v[42:43], s[92:93] op_sel_hi:[1,0]
	v_cvt_pk_bf16_f32 v133, v42, v43
	v_lshlrev_b32_e32 v40, 16, v26
	v_and_b32_e32 v41, 0xffff0000, v26
	v_pk_mul_f32 v[40:41], v[40:41], s[92:93] op_sel_hi:[1,0]
	v_cvt_pk_bf16_f32 v134, v40, v41
	v_lshlrev_b32_e32 v42, 16, v27
	v_and_b32_e32 v43, 0xffff0000, v27
	v_pk_mul_f32 v[42:43], v[42:43], s[92:93] op_sel_hi:[1,0]
	v_cvt_pk_bf16_f32 v135, v42, v43
	v_lshlrev_b32_e32 v40, 16, v28
	v_and_b32_e32 v41, 0xffff0000, v28
	v_pk_mul_f32 v[40:41], v[40:41], s[92:93] op_sel_hi:[1,0]
	v_cvt_pk_bf16_f32 v136, v40, v41
	v_lshlrev_b32_e32 v42, 16, v29
	v_and_b32_e32 v43, 0xffff0000, v29
	v_pk_mul_f32 v[42:43], v[42:43], s[92:93] op_sel_hi:[1,0]
	v_cvt_pk_bf16_f32 v137, v42, v43
	v_lshlrev_b32_e32 v40, 16, v30
	v_and_b32_e32 v41, 0xffff0000, v30
	v_pk_mul_f32 v[40:41], v[40:41], s[92:93] op_sel_hi:[1,0]
	v_cvt_pk_bf16_f32 v138, v40, v41
	v_lshlrev_b32_e32 v42, 16, v31
	v_and_b32_e32 v43, 0xffff0000, v31
	v_pk_mul_f32 v[42:43], v[42:43], s[92:93] op_sel_hi:[1,0]
	v_cvt_pk_bf16_f32 v139, v42, v43
	v_lshlrev_b32_e32 v40, 16, v36
	v_and_b32_e32 v41, 0xffff0000, v36
	v_pk_mul_f32 v[40:41], v[40:41], s[92:93] op_sel_hi:[1,0]
	v_cvt_pk_bf16_f32 v140, v40, v41
	v_lshlrev_b32_e32 v42, 16, v37
	v_and_b32_e32 v43, 0xffff0000, v37
	v_pk_mul_f32 v[42:43], v[42:43], s[92:93] op_sel_hi:[1,0]
	v_cvt_pk_bf16_f32 v141, v42, v43
	v_lshlrev_b32_e32 v40, 16, v38
	v_and_b32_e32 v41, 0xffff0000, v38
	v_pk_mul_f32 v[40:41], v[40:41], s[92:93] op_sel_hi:[1,0]
	v_cvt_pk_bf16_f32 v142, v40, v41
	v_lshlrev_b32_e32 v42, 16, v39
	v_and_b32_e32 v43, 0xffff0000, v39
	v_pk_mul_f32 v[42:43], v[42:43], s[92:93] op_sel_hi:[1,0]
	v_cvt_pk_bf16_f32 v143, v42, v43
	v_and_b32_e32 v45, 0xffff0000, v140
	v_add3_u32 v16, 0, v224, v223
	s_barrier
	s_waitcnt vmcnt(5)
	ds_write_b128 v16, v[0:3]
	v_mul_lo_u32 v2, v34, 48
	v_add_u32_e32 v0, v16, v2
	s_waitcnt vmcnt(4)
	ds_write_b128 v0, v[4:7] offset:9216
	v_mad_u64_u32 v[0:1], s[4:5], v34, s4, v[0:1]
	s_waitcnt vmcnt(3)
	ds_write_b128 v0, v[8:11] offset:21504
	v_add_u32_e32 v0, v0, v2
	v_readlane_b32 s4, v255, 48
	s_waitcnt vmcnt(2)
	ds_write_b128 v0, v[12:15] offset:30720
	s_waitcnt lgkmcnt(0)
	s_barrier
; __device__ __forceinline__ float bflo(unsigned u) { return __uint_as_float(u << 16); }
; __device__ __forceinline__ float bfhi(unsigned u) { return __uint_as_float(u & 0xffff0000u); }
; #define WRITE_TILE(bufp) do { LAS unsigned char* _k = (bufp); LAS unsigned char* _v = (bufp) + 64 * KST; \
;         *(LAS u32x4*)(_k + key * KST + ch * 16) = kreg; \
;         *(LAS u32x4*)(_v + key * VST + ch * 16) = vreg; } while (0)
; #define QK_TILE(kbp, d0, d1) do { _Pragma("unroll") for (int s = 0; s < 4; ++s) { \
;         const bf16x8 _k0 = *(const LAS bf16x8*)((kbp) + ql * KST + hh * 16 + 32 * s), _k1 = *(const LAS bf16x8*)((kbp) + (32 + ql) * KST + hh * 16 + 32 * s); \
;         d0 = MFMA32(_k0, qf[s], d0); d1 = MFMA32(_k1, qf[s], d1); } } while (0)
; __device__ __forceinline__ void attnB_unit(LAS unsigned char* lds, const Args& A, int unit, const float* kng, bool do_store = true) {
;     ...
;     __syncthreads();
;     WRITE_TILE(lds);
;     kreg = kq1; vreg = vq1;
;     WRITE_TILE(lds + BUF_B);
;     __syncthreads();
;     constexpr int NT = SEQ / 64;
;     f32x16 c0, c1, d0, d1, o2;
; #pragma unroll
;     for (int i = 0; i < 16; ++i) { c0[i] = 0.f; c1[i] = 0.f; o2[i] = 0.f; }
;     QK_TILE(lds, c0, c1);
;     float mx = fmaxf(c0[0], c1[0]);
; #pragma unroll
;     for (int i = 1; i < 16; ++i) mx = fmaxf(mx, fmaxf(c0[i], c1[i]));
;     mx = fmaxf(mx, __shfl_xor(mx, 32));
;     float qn2 = 0.f;
; #pragma unroll
;     for (int s = 0; s < 4; ++s) { const u32x4 qw = __builtin_bit_cast(u32x4, qf[s]);
;         qn2 += bflo(qw.x) * bflo(qw.x) + bfhi(qw.x) * bfhi(qw.x) + bflo(qw.y) * bflo(qw.y) + bfhi(qw.y) * bfhi(qw.y) + bflo(qw.z) * bflo(qw.z) + bfhi(qw.z) * bfhi(qw.z) + bflo(qw.w) * bflo(qw.w) + bfhi(qw.w) * bfhi(qw.w); }
;     qn2 += __shfl_xor(qn2, 32);
;     float gk = fabsf(kng[lane]);
; #pragma unroll
;     for (int o = 1; o < 64; o <<= 1) gk = fmaxf(gk, __shfl_xor(gk, o));
;     const bool fast = __all(sqrtf(qn2) * 8.0f * gk * 1.05f <= 48.0f) != 0;
	ds_read_b128 v[0:3], v44 offset:4608
	ds_read_b128 v[4:7], v44
	ds_read_b128 v[36:39], v44 offset:32
	ds_read_b128 v[40:43], v44 offset:4640
	s_waitcnt lgkmcnt(2)
	v_mfma_f32_32x32x16_bf16 v[16:31], v[4:7], v[128:131], 0
	v_readlane_b32 s5, v255, 49
	v_mfma_f32_32x32x16_bf16 v[0:15], v[0:3], v[128:131], 0
	s_waitcnt lgkmcnt(1)
	v_mfma_f32_32x32x16_bf16 v[16:31], v[36:39], v[132:135], v[16:31]
	s_waitcnt lgkmcnt(0)
	v_mfma_f32_32x32x16_bf16 v[0:15], v[40:43], v[132:135], v[0:15]
	ds_read_b128 v[36:39], v44 offset:64
	ds_read_b128 v[40:43], v44 offset:4672
	s_waitcnt lgkmcnt(1)
	v_mfma_f32_32x32x16_bf16 v[16:31], v[36:39], v[136:139], v[16:31]
	s_waitcnt lgkmcnt(0)
	v_mfma_f32_32x32x16_bf16 v[0:15], v[40:43], v[136:139], v[0:15]
	ds_read_b128 v[36:39], v44 offset:96
	ds_read_b128 v[40:43], v44 offset:4704
	v_and_b32_e32 v44, 0xffff0000, v136
	v_mul_f32_e64 v44, v44, v44
	v_mul_f32_e64 v45, v45, v45
	s_mov_b32 s4, 0xf800000
	s_waitcnt lgkmcnt(1)
	v_mfma_f32_32x32x16_bf16 v[16:31], v[36:39], v[140:143], v[16:31]
	s_waitcnt lgkmcnt(0)
	v_mfma_f32_32x32x16_bf16 v[0:15], v[40:43], v[140:143], v[0:15]
	s_nop 9
	v_max_f32_e32 v37, v17, v17
	v_max_f32_e32 v38, v18, v18
	v_max_f32_e32 v39, v19, v19
	v_and_b32_e32 v43, 0xffff0000, v132
	v_and_b32_e32 v42, 0xffff0000, v128
	v_lshlrev_b32_e32 v41, 16, v132
	v_lshlrev_b32_e32 v40, 16, v128
	v_max_f32_e32 v36, v1, v1
	v_max_f32_e32 v36, v37, v36
	v_max_f32_e32 v37, v2, v2
	v_max_f32_e32 v37, v38, v37
	v_max_f32_e32 v38, v3, v3
	v_max3_f32 v36, v16, v0, v36
	v_max_f32_e32 v38, v39, v38
	v_max3_f32 v36, v36, v37, v38
	v_max_f32_e32 v37, v4, v4
	v_max_f32_e32 v38, v20, v20
	v_max_f32_e32 v37, v38, v37
	v_max_f32_e32 v38, v5, v5
	v_max_f32_e32 v39, v21, v21
	v_max_f32_e32 v38, v39, v38
	v_max3_f32 v36, v36, v37, v38
	v_max_f32_e32 v37, v6, v6
	v_max_f32_e32 v38, v22, v22
	v_max_f32_e32 v37, v38, v37
	v_max_f32_e32 v38, v7, v7
	v_max_f32_e32 v39, v23, v23
	v_max_f32_e32 v38, v39, v38
	v_pk_mul_f32 v[42:43], v[42:43], v[42:43]
	v_max3_f32 v36, v36, v37, v38
	v_max_f32_e32 v37, v8, v8
	v_max_f32_e32 v38, v24, v24
	v_pk_fma_f32 v[40:41], v[40:41], v[40:41], v[42:43]
	v_lshlrev_b32_e32 v42, 16, v129
	v_lshlrev_b32_e32 v43, 16, v133
	v_max_f32_e32 v37, v38, v37
	v_max_f32_e32 v38, v9, v9
	v_max_f32_e32 v39, v25, v25
	v_pk_fma_f32 v[40:41], v[42:43], v[42:43], v[40:41]
	v_and_b32_e32 v43, 0xffff0000, v133
	v_and_b32_e32 v42, 0xffff0000, v129
	v_max_f32_e32 v38, v39, v38
	v_pk_fma_f32 v[40:41], v[42:43], v[42:43], v[40:41]
	v_lshlrev_b32_e32 v43, 16, v134
	v_lshlrev_b32_e32 v42, 16, v130
	v_max3_f32 v36, v36, v37, v38
	v_max_f32_e32 v37, v10, v10
	v_max_f32_e32 v38, v26, v26
	v_pk_fma_f32 v[40:41], v[42:43], v[42:43], v[40:41]
	v_and_b32_e32 v43, 0xffff0000, v134
	v_and_b32_e32 v42, 0xffff0000, v130
	v_max_f32_e32 v37, v38, v37
	v_max_f32_e32 v38, v11, v11
	v_max_f32_e32 v39, v27, v27
	v_pk_fma_f32 v[40:41], v[42:43], v[42:43], v[40:41]
	v_lshlrev_b32_e32 v43, 16, v135
	v_lshlrev_b32_e32 v42, 16, v131
	v_max_f32_e32 v38, v39, v38
	v_pk_fma_f32 v[40:41], v[42:43], v[42:43], v[40:41]
	v_and_b32_e32 v43, 0xffff0000, v135
	v_and_b32_e32 v42, 0xffff0000, v131
	v_max3_f32 v36, v36, v37, v38
	v_max_f32_e32 v37, v12, v12
	v_max_f32_e32 v38, v28, v28
	v_pk_fma_f32 v[40:41], v[42:43], v[42:43], v[40:41]
	v_lshlrev_b32_e32 v43, 16, v140
	v_lshlrev_b32_e32 v42, 16, v136
	v_max_f32_e32 v37, v38, v37
	v_max_f32_e32 v38, v13, v13
	v_max_f32_e32 v39, v29, v29
	v_pk_fma_f32 v[42:43], v[42:43], v[42:43], v[44:45]
	v_lshlrev_b32_e32 v44, 16, v137
	v_lshlrev_b32_e32 v45, 16, v141
	v_max_f32_e32 v38, v39, v38
	v_pk_fma_f32 v[42:43], v[44:45], v[44:45], v[42:43]
	v_and_b32_e32 v45, 0xffff0000, v141
	v_and_b32_e32 v44, 0xffff0000, v137
	v_max3_f32 v36, v36, v37, v38
	v_max_f32_e32 v37, v14, v14
	v_max_f32_e32 v38, v30, v30
	v_pk_fma_f32 v[42:43], v[44:45], v[44:45], v[42:43]
	v_lshlrev_b32_e32 v45, 16, v142
	v_lshlrev_b32_e32 v44, 16, v138
	v_max_f32_e32 v37, v38, v37
	v_max_f32_e32 v38, v15, v15
	v_max_f32_e32 v39, v31, v31
	v_pk_fma_f32 v[42:43], v[44:45], v[44:45], v[42:43]
	v_and_b32_e32 v45, 0xffff0000, v142
	v_and_b32_e32 v44, 0xffff0000, v138
	v_max_f32_e32 v38, v39, v38
	v_pk_fma_f32 v[42:43], v[44:45], v[44:45], v[42:43]
	v_lshlrev_b32_e32 v45, 16, v143
	v_lshlrev_b32_e32 v44, 16, v139
	v_max3_f32 v36, v36, v37, v38
	v_and_b32_e32 v38, 64, v217
	v_pk_fma_f32 v[42:43], v[44:45], v[44:45], v[42:43]
	v_and_b32_e32 v45, 0xffff0000, v143
	v_and_b32_e32 v44, 0xffff0000, v139
	v_xor_b32_e32 v37, 32, v217
	v_add_u32_e32 v38, 64, v38
	v_pk_fma_f32 v[42:43], v[44:45], v[44:45], v[42:43]
	v_add_f32_e32 v39, v40, v41
	v_cmp_lt_i32_e32 vcc, v37, v38
	v_add_f32_e32 v39, v39, v42
	v_xor_b32_e32 v42, 1, v217
	v_cndmask_b32_e32 v37, v217, v37, vcc
	v_cmp_lt_i32_e32 vcc, v42, v38
	s_waitcnt vmcnt(0)
; __device__ __forceinline__ float bflo(unsigned u) { return __uint_as_float(u << 16); }
; __device__ __forceinline__ float bfhi(unsigned u) { return __uint_as_float(u & 0xffff0000u); }
; __device__ __forceinline__ void attnB_unit(LAS unsigned char* lds, const Args& A, int unit, const float* kng, bool do_store = true) {
;     ...
;     float mx = fmaxf(c0[0], c1[0]);
; #pragma unroll
;     for (int i = 1; i < 16; ++i) mx = fmaxf(mx, fmaxf(c0[i], c1[i]));
;     mx = fmaxf(mx, __shfl_xor(mx, 32));
;     float qn2 = 0.f;
; #pragma unroll
;     for (int s = 0; s < 4; ++s) { const u32x4 qw = __builtin_bit_cast(u32x4, qf[s]);
;         qn2 += bflo(qw.x) * bflo(qw.x) + bfhi(qw.x) * bfhi(qw.x) + bflo(qw.y) * bflo(qw.y) + bfhi(qw.y) * bfhi(qw.y) + bflo(qw.z) * bflo(qw.z) + bfhi(qw.z) * bfhi(qw.z) + bflo(qw.w) * bflo(qw.w) + bfhi(qw.w) * bfhi(qw.w); }
;     qn2 += __shfl_xor(qn2, 32);
;     float gk = fabsf(kng[lane]);
; #pragma unroll
;     for (int o = 1; o < 64; o <<= 1) gk = fmaxf(gk, __shfl_xor(gk, o));
;     const bool fast = __all(sqrtf(qn2) * 8.0f * gk * 1.05f <= 48.0f) != 0;
;     if (fast) { m_used = 0.f; mx = 0.f; }
;     else {
;         m_used = mx;
; #pragma unroll
;         for (int i = 0; i < 16; ++i) { c0[i] -= m_used; c1[i] -= m_used; }
;         mx = 0.f;
;     }
	v_and_b32_e32 v41, 0x7fffffff, v35
	v_max_f32_e64 v35, |v35|, |v35|
	v_cndmask_b32_e32 v42, v217, v42, vcc
	v_lshlrev_b32_e32 v42, 2, v42
	ds_bpermute_b32 v41, v42, v41
	v_lshlrev_b32_e32 v226, 2, v37
	v_add_f32_e32 v39, v39, v43
	ds_bpermute_b32 v40, v226, v39
	ds_bpermute_b32 v37, v226, v36
	s_waitcnt lgkmcnt(2)
	v_max_f32_e32 v41, v41, v41
	v_max_f32_e32 v35, v35, v41
	v_xor_b32_e32 v41, 2, v217
	v_cmp_lt_i32_e32 vcc, v41, v38
	s_nop 1
	v_cndmask_b32_e32 v41, v217, v41, vcc
	v_lshlrev_b32_e32 v41, 2, v41
	ds_bpermute_b32 v41, v41, v35
	s_waitcnt lgkmcnt(0)
	v_max_f32_e32 v41, v41, v41
	v_max_f32_e32 v35, v35, v41
	v_xor_b32_e32 v41, 4, v217
	v_cmp_lt_i32_e32 vcc, v41, v38
	s_nop 1
	v_cndmask_b32_e32 v41, v217, v41, vcc
	v_lshlrev_b32_e32 v41, 2, v41
	ds_bpermute_b32 v41, v41, v35
	s_waitcnt lgkmcnt(0)
	v_max_f32_e32 v41, v41, v41
	v_max_f32_e32 v35, v35, v41
	v_xor_b32_e32 v41, 8, v217
	v_cmp_lt_i32_e32 vcc, v41, v38
	s_nop 1
	v_cndmask_b32_e32 v41, v217, v41, vcc
	v_lshlrev_b32_e32 v41, 2, v41
	ds_bpermute_b32 v41, v41, v35
	s_waitcnt lgkmcnt(0)
	v_max_f32_e32 v41, v41, v41
	v_max_f32_e32 v35, v35, v41
	v_xor_b32_e32 v41, 16, v217
	v_cmp_lt_i32_e32 vcc, v41, v38
	s_nop 1
	v_cndmask_b32_e32 v38, v217, v41, vcc
	v_lshlrev_b32_e32 v38, 2, v38
	ds_bpermute_b32 v38, v38, v35
	s_waitcnt lgkmcnt(0)
	v_max_f32_e32 v38, v38, v38
	v_max_f32_e32 v35, v35, v38
	ds_bpermute_b32 v38, v226, v35
	s_waitcnt lgkmcnt(0)
	v_max_f32_e32 v38, v38, v38
	v_max_f32_e32 v35, v35, v38
	v_add_f32_e32 v38, v39, v40
	v_cmp_gt_f32_e32 vcc, s4, v38
	v_mul_f32_e32 v39, 0x4f800000, v38
	s_nop 0
	v_cndmask_b32_e32 v38, v38, v39, vcc
	v_sqrt_f32_e32 v39, v38
	s_nop 0
	v_add_u32_e32 v40, -1, v39
	v_fma_f32 v41, -v40, v39, v38
	v_cmp_ge_f32_e64 s[4:5], 0, v41
	v_add_u32_e32 v41, 1, v39
	s_nop 0
	v_cndmask_b32_e64 v40, v39, v40, s[4:5]
	v_fma_f32 v39, -v41, v39, v38
	v_cmp_lt_f32_e64 s[4:5], 0, v39
	s_nop 1
	v_cndmask_b32_e64 v39, v40, v41, s[4:5]
	v_mul_f32_e32 v40, 0x37800000, v39
	v_cndmask_b32_e32 v39, v39, v40, vcc
	v_cmp_class_f32_e32 vcc, v38, v216
	s_mov_b32 s4, 0x42400000
	s_nop 0
	v_cndmask_b32_e32 v38, v39, v38, vcc
	v_mul_f32_e32 v38, 0x41000000, v38
	v_mul_f32_e32 v35, v38, v35
	v_mul_f32_e32 v35, 0x3f866666, v35
	v_cmp_ge_f32_e32 vcc, s4, v35
	s_cmp_lg_u64 vcc, exec
	s_cselect_b64 s[4:5], -1, 0
	s_cmp_eq_u64 vcc, exec
	s_cbranch_scc1 .LBB0_316
	v_max_f32_e32 v35, v37, v37
	v_max_f32_e32 v36, v36, v36
	v_max_f32_e32 v172, v36, v35
	v_sub_f32_e32 v31, v31, v172
	v_sub_f32_e32 v30, v30, v172
	v_sub_f32_e32 v29, v29, v172
	v_sub_f32_e32 v28, v28, v172
	v_sub_f32_e32 v27, v27, v172
	v_sub_f32_e32 v26, v26, v172
	v_sub_f32_e32 v25, v25, v172
	v_sub_f32_e32 v24, v24, v172
	v_sub_f32_e32 v23, v23, v172
	v_sub_f32_e32 v22, v22, v172
	v_sub_f32_e32 v21, v21, v172
	v_sub_f32_e32 v20, v20, v172
	v_sub_f32_e32 v19, v19, v172
	v_sub_f32_e32 v18, v18, v172
	v_sub_f32_e32 v17, v17, v172
	v_sub_f32_e32 v16, v16, v172
	v_sub_f32_e32 v15, v15, v172
	v_sub_f32_e32 v14, v14, v172
	v_sub_f32_e32 v13, v13, v172
	v_sub_f32_e32 v12, v12, v172
	v_sub_f32_e32 v11, v11, v172
	v_sub_f32_e32 v10, v10, v172
	v_sub_f32_e32 v9, v9, v172
	v_sub_f32_e32 v8, v8, v172
	v_sub_f32_e32 v7, v7, v172
	v_sub_f32_e32 v6, v6, v172
	v_sub_f32_e32 v5, v5, v172
	v_sub_f32_e32 v4, v4, v172
	v_sub_f32_e32 v3, v3, v172
	v_sub_f32_e32 v2, v2, v172
	v_sub_f32_e32 v1, v1, v172
	v_sub_f32_e32 v0, v0, v172

; __device__ __forceinline__ void attnB_unit(LAS unsigned char* lds, const Args& A, int unit, const float* kng, bool do_store = true) {
;     ...
;     const short one_bits = ql == 0 ? (short)0x3F80 : (short)0;
;     const bf16x8 ones = {one_bits, one_bits, one_bits, one_bits, one_bits, one_bits, one_bits, one_bits};
;     int rb = 0;
.LBB0_324:
	s_and_b64 vcc, exec, s[6:7]
	s_cbranch_vccz .LBB0_275
	v_readfirstlane_b32 s4, v168
	v_readfirstlane_b32 s5, v169
	v_readfirstlane_b32 s6, v170
	v_readfirstlane_b32 s7, v171
	v_mov_b32_e32 v32, 0
	v_mov_b32_e32 v33, v32
	v_mov_b32_e32 v34, v32
	v_mov_b32_e32 v35, v32
	v_mov_b32_e32 v36, v32
	v_mov_b32_e32 v37, v32
	v_mov_b32_e32 v38, v32
	v_mov_b32_e32 v39, v32
	v_mov_b32_e32 v40, v32
	v_mov_b32_e32 v41, v32
	v_mov_b32_e32 v42, v32
	v_mov_b32_e32 v43, v32
	v_mov_b32_e32 v44, v32
	v_mov_b32_e32 v45, v32
	v_mov_b32_e32 v46, v32
	v_mov_b32_e32 v47, v32
	v_mov_b32_e32 v48, v32
	v_mov_b32_e32 v49, v32
	v_mov_b32_e32 v50, v32
	v_mov_b32_e32 v51, v32
	v_mov_b32_e32 v52, v32
	v_mov_b32_e32 v53, v32
	v_mov_b32_e32 v54, v32
	v_mov_b32_e32 v55, v32
	v_mov_b32_e32 v56, v32
	v_mov_b32_e32 v57, v32
	v_mov_b32_e32 v58, v32
	v_mov_b32_e32 v59, v32
	v_mov_b32_e32 v60, v32
	v_mov_b32_e32 v61, v32
	v_mov_b32_e32 v62, v32
	v_mov_b32_e32 v63, v32
	v_mov_b32_e32 v174, v32
	v_mov_b32_e32 v175, v32
	v_mov_b32_e32 v176, v32
	v_mov_b32_e32 v177, v32
	v_add_u32_e32 v172, v225, v184
	v_add_u32_e32 v173, 0xa800, v172
	v_mov_b32_e32 v182, v232
	v_add_u32_e32 v183, 0xa800, v232
	v_add_u32_e32 v186, v224, v223
	v_add_u32_e32 v187, 0xa800, v186
	v_add_u32_e32 v188, v228, v223
	v_add_u32_e32 v189, 0xa800, v188
	v_and_b32_e32 v218, 31, v217
	v_mov_b32_e32 v219, 0x3f803f80
	v_cmp_eq_u32_e32 vcc, 0, v218
	s_nop 1
	v_cndmask_b32_e32 v178, 0, v219, vcc
	v_cmp_eq_u32_e32 vcc, 17, v218
	s_nop 1
	v_cndmask_b32_e32 v178, v178, v219, vcc
	v_mov_b32_e32 v179, v178
	v_mov_b32_e32 v180, v178
	v_mov_b32_e32 v181, v178
	v_lshlrev_b32_e32 v214, 4, v217
	v_add_u32_e32 v214, 0x4000, v214
	s_mov_b32 s11, 31
	ds_read_b64_tr_b16 v[160:161], v182 offset:9216
	ds_read_b64_tr_b16 v[162:163], v182 offset:10752
	ds_read_b64_tr_b16 v[164:165], v182 offset:9280
	ds_read_b64_tr_b16 v[166:167], v182 offset:10816
	ds_read_b64_tr_b16 v[190:191], v182 offset:12288
	ds_read_b64_tr_b16 v[192:193], v182 offset:13824
	ds_read_b64_tr_b16 v[194:195], v182 offset:12352
	ds_read_b64_tr_b16 v[196:197], v182 offset:13888
	v_exp_f32_e32 v16, v16
	v_exp_f32_e32 v17, v17
	v_exp_f32_e32 v18, v18
	v_cvt_pk_bf16_f32 v238, v16, v17
	v_exp_f32_e32 v19, v19
	v_exp_f32_e32 v20, v20
	v_cvt_pk_bf16_f32 v239, v18, v19
	v_exp_f32_e32 v21, v21
	v_exp_f32_e32 v22, v22
	v_cvt_pk_bf16_f32 v240, v20, v21
	v_exp_f32_e32 v23, v23
	v_exp_f32_e32 v24, v24
	v_cvt_pk_bf16_f32 v241, v22, v23
	v_exp_f32_e32 v25, v25
	v_exp_f32_e32 v26, v26
	v_cvt_pk_bf16_f32 v242, v24, v25
	v_exp_f32_e32 v27, v27
	v_exp_f32_e32 v28, v28
	v_cvt_pk_bf16_f32 v243, v26, v27
	v_exp_f32_e32 v29, v29
	s_waitcnt lgkmcnt(0)
.Lmixb_loop:
	v_mfma_f32_32x32x16_bf16 v[32:47], v[160:163], v[238:241], v[32:47]
	ds_read_b128 v[96:99], v172 offset:21504
	ds_read_b128 v[100:103], v172 offset:21536
	ds_read_b128 v[104:107], v172 offset:21568
	ds_read_b128 v[108:111], v172 offset:21600
	v_exp_f32_e32 v30, v30
	v_cvt_pk_bf16_f32 v244, v28, v29
	v_exp_f32_e32 v31, v31
	v_mfma_f32_32x32x16_bf16 v[48:63], v[164:167], v[238:241], v[48:63]
	v_mfma_f32_16x16x32_bf16 v[174:177], v[178:181], v[238:241], v[174:177]
	ds_read_b128 v[112:115], v172 offset:26112
	ds_read_b128 v[116:119], v172 offset:26144
	ds_read_b128 v[120:123], v172 offset:26176
	ds_read_b128 v[124:127], v172 offset:26208
	v_exp_f32_e32 v0, v0
	v_cvt_pk_bf16_f32 v245, v30, v31
	v_exp_f32_e32 v1, v1
	v_add_u32_e32 v214, 0x2000, v214
	global_load_dwordx4 v[152:155], v214, s[4:5]
	global_load_dwordx4 v[156:159], v214, s[6:7]
	v_mfma_f32_32x32x16_bf16 v[32:47], v[190:193], v[242:245], v[32:47]
	v_exp_f32_e32 v2, v2
	v_cvt_pk_bf16_f32 v246, v0, v1
	v_exp_f32_e32 v3, v3
	ds_read_b64_tr_b16 v[198:199], v182 offset:15360
	ds_read_b64_tr_b16 v[200:201], v182 offset:16896
	v_mfma_f32_32x32x16_bf16 v[48:63], v[194:197], v[242:245], v[48:63]
	v_mfma_f32_16x16x32_bf16 v[174:177], v[178:181], v[242:245], v[174:177]
	v_exp_f32_e32 v4, v4
	v_cvt_pk_bf16_f32 v247, v2, v3
	v_exp_f32_e32 v5, v5
	ds_read_b64_tr_b16 v[202:203], v182 offset:15424
	ds_read_b64_tr_b16 v[204:205], v182 offset:16960
	s_waitcnt lgkmcnt(8)
	v_mfma_f32_32x32x16_bf16 v[80:95], v[96:99], v[128:131], 0
	v_exp_f32_e32 v6, v6
	v_cvt_pk_bf16_f32 v248, v4, v5
	v_exp_f32_e32 v7, v7
	ds_read_b64_tr_b16 v[206:207], v182 offset:18432
	ds_read_b64_tr_b16 v[208:209], v182 offset:19968
	v_mfma_f32_32x32x16_bf16 v[80:95], v[100:103], v[132:135], v[80:95]
	v_exp_f32_e32 v8, v8
	v_cvt_pk_bf16_f32 v249, v6, v7
	v_exp_f32_e32 v9, v9
	ds_read_b64_tr_b16 v[234:235], v182 offset:18496
	ds_read_b64_tr_b16 v[236:237], v182 offset:20032
	v_mfma_f32_32x32x16_bf16 v[80:95], v[104:107], v[136:139], v[80:95]
	v_exp_f32_e32 v10, v10
	v_cvt_pk_bf16_f32 v250, v8, v9
	v_exp_f32_e32 v11, v11
	ds_read_b64_tr_b16 v[160:161], v182 offset:30720
	ds_read_b64_tr_b16 v[162:163], v182 offset:32256
	v_mfma_f32_32x32x16_bf16 v[80:95], v[108:111], v[140:143], v[80:95]
	v_exp_f32_e32 v12, v12
	v_cvt_pk_bf16_f32 v251, v10, v11
	v_exp_f32_e32 v13, v13
	ds_read_b64_tr_b16 v[164:165], v182 offset:30784
	ds_read_b64_tr_b16 v[166:167], v182 offset:32320
	s_waitcnt lgkmcnt(12)
	v_mfma_f32_32x32x16_bf16 v[64:79], v[112:115], v[128:131], 0
	v_exp_f32_e32 v14, v14
	v_cvt_pk_bf16_f32 v252, v12, v13
	v_exp_f32_e32 v15, v15
	ds_read_b64_tr_b16 v[190:191], v182 offset:33792
	ds_read_b64_tr_b16 v[192:193], v182 offset:35328
	v_mfma_f32_32x32x16_bf16 v[64:79], v[116:119], v[132:135], v[64:79]
	v_exp_f32_e32 v80, v80
	v_cvt_pk_bf16_f32 v253, v14, v15
	v_exp_f32_e32 v81, v81
	ds_read_b64_tr_b16 v[194:195], v182 offset:33856
	ds_read_b64_tr_b16 v[196:197], v182 offset:35392
	v_mfma_f32_32x32x16_bf16 v[64:79], v[120:123], v[136:139], v[64:79]
	v_exp_f32_e32 v82, v82
	v_cvt_pk_bf16_f32 v238, v80, v81
	v_exp_f32_e32 v83, v83
	s_waitcnt vmcnt(2)
	ds_write_b128 v187, v[144:147]
	v_mfma_f32_32x32x16_bf16 v[64:79], v[124:127], v[140:143], v[64:79]
	v_exp_f32_e32 v84, v84
	v_cvt_pk_bf16_f32 v239, v82, v83
	v_exp_f32_e32 v85, v85
	ds_write_b128 v189, v[148:151] offset:9216
	s_waitcnt lgkmcnt(10)
	v_mfma_f32_32x32x16_bf16 v[32:47], v[198:201], v[246:249], v[32:47]
	v_exp_f32_e32 v86, v86
	v_cvt_pk_bf16_f32 v240, v84, v85
	v_exp_f32_e32 v87, v87
	v_mfma_f32_32x32x16_bf16 v[48:63], v[202:205], v[246:249], v[48:63]
	v_mfma_f32_16x16x32_bf16 v[174:177], v[178:181], v[246:249], v[174:177]
	v_exp_f32_e32 v88, v88
	v_cvt_pk_bf16_f32 v241, v86, v87
	v_exp_f32_e32 v89, v89
	v_mfma_f32_32x32x16_bf16 v[32:47], v[206:209], v[250:253], v[32:47]
	v_exp_f32_e32 v90, v90
	v_cvt_pk_bf16_f32 v242, v88, v89
	v_exp_f32_e32 v91, v91
	v_mfma_f32_32x32x16_bf16 v[48:63], v[234:237], v[250:253], v[48:63]
	v_mfma_f32_16x16x32_bf16 v[174:177], v[178:181], v[250:253], v[174:177]
	v_exp_f32_e32 v92, v92
	v_cvt_pk_bf16_f32 v243, v90, v91
	v_exp_f32_e32 v93, v93
	s_waitcnt lgkmcnt(0)
	s_barrier
	v_mfma_f32_32x32x16_bf16 v[32:47], v[160:163], v[238:241], v[32:47]
	ds_read_b128 v[96:99], v173
	ds_read_b128 v[100:103], v173 offset:32
	ds_read_b128 v[104:107], v173 offset:64
	ds_read_b128 v[108:111], v173 offset:96
	v_exp_f32_e32 v94, v94
	v_cvt_pk_bf16_f32 v244, v92, v93
	v_exp_f32_e32 v95, v95
	v_mfma_f32_32x32x16_bf16 v[48:63], v[164:167], v[238:241], v[48:63]
	v_mfma_f32_16x16x32_bf16 v[174:177], v[178:181], v[238:241], v[174:177]
	ds_read_b128 v[112:115], v173 offset:4608
	ds_read_b128 v[116:119], v173 offset:4640
	ds_read_b128 v[120:123], v173 offset:4672
	ds_read_b128 v[124:127], v173 offset:4704
	v_exp_f32_e32 v64, v64
	v_cvt_pk_bf16_f32 v245, v94, v95
	v_exp_f32_e32 v65, v65
	v_add_u32_e32 v214, 0x2000, v214
	global_load_dwordx4 v[144:147], v214, s[4:5]
	global_load_dwordx4 v[148:151], v214, s[6:7]
	v_mfma_f32_32x32x16_bf16 v[32:47], v[190:193], v[242:245], v[32:47]
	v_exp_f32_e32 v66, v66
	v_cvt_pk_bf16_f32 v246, v64, v65
	v_exp_f32_e32 v67, v67
	ds_read_b64_tr_b16 v[198:199], v182 offset:36864
	ds_read_b64_tr_b16 v[200:201], v182 offset:38400
	v_mfma_f32_32x32x16_bf16 v[48:63], v[194:197], v[242:245], v[48:63]
	v_mfma_f32_16x16x32_bf16 v[174:177], v[178:181], v[242:245], v[174:177]
	v_exp_f32_e32 v68, v68
	v_cvt_pk_bf16_f32 v247, v66, v67
	v_exp_f32_e32 v69, v69
	ds_read_b64_tr_b16 v[202:203], v182 offset:36928
	ds_read_b64_tr_b16 v[204:205], v182 offset:38464
	s_waitcnt lgkmcnt(8)
	v_mfma_f32_32x32x16_bf16 v[16:31], v[96:99], v[128:131], 0
	v_exp_f32_e32 v70, v70
	v_cvt_pk_bf16_f32 v248, v68, v69
	v_exp_f32_e32 v71, v71
	ds_read_b64_tr_b16 v[206:207], v182 offset:39936
	ds_read_b64_tr_b16 v[208:209], v182 offset:41472
	v_mfma_f32_32x32x16_bf16 v[16:31], v[100:103], v[132:135], v[16:31]
	v_exp_f32_e32 v72, v72
	v_cvt_pk_bf16_f32 v249, v70, v71
	v_exp_f32_e32 v73, v73
	ds_read_b64_tr_b16 v[234:235], v182 offset:40000
	ds_read_b64_tr_b16 v[236:237], v182 offset:41536
	v_mfma_f32_32x32x16_bf16 v[16:31], v[104:107], v[136:139], v[16:31]
	v_exp_f32_e32 v74, v74
	v_cvt_pk_bf16_f32 v250, v72, v73
	v_exp_f32_e32 v75, v75
	ds_read_b64_tr_b16 v[160:161], v183 offset:9216
	ds_read_b64_tr_b16 v[162:163], v183 offset:10752
	v_mfma_f32_32x32x16_bf16 v[16:31], v[108:111], v[140:143], v[16:31]
	v_exp_f32_e32 v76, v76
	v_cvt_pk_bf16_f32 v251, v74, v75
	v_exp_f32_e32 v77, v77
	ds_read_b64_tr_b16 v[164:165], v183 offset:9280
	ds_read_b64_tr_b16 v[166:167], v183 offset:10816
	s_waitcnt lgkmcnt(12)
	v_mfma_f32_32x32x16_bf16 v[0:15], v[112:115], v[128:131], 0
	v_exp_f32_e32 v78, v78
	v_cvt_pk_bf16_f32 v252, v76, v77
	v_exp_f32_e32 v79, v79
	ds_read_b64_tr_b16 v[190:191], v183 offset:12288
	ds_read_b64_tr_b16 v[192:193], v183 offset:13824
	v_mfma_f32_32x32x16_bf16 v[0:15], v[116:119], v[132:135], v[0:15]
	v_exp_f32_e32 v16, v16
	v_cvt_pk_bf16_f32 v253, v78, v79
	v_exp_f32_e32 v17, v17
	ds_read_b64_tr_b16 v[194:195], v183 offset:12352
	ds_read_b64_tr_b16 v[196:197], v183 offset:13888
	v_mfma_f32_32x32x16_bf16 v[0:15], v[120:123], v[136:139], v[0:15]
	v_exp_f32_e32 v18, v18
	v_cvt_pk_bf16_f32 v238, v16, v17
	v_exp_f32_e32 v19, v19
	s_waitcnt vmcnt(2)
	ds_write_b128 v187, v[152:155] offset:21504
	v_mfma_f32_32x32x16_bf16 v[0:15], v[124:127], v[140:143], v[0:15]
	v_exp_f32_e32 v20, v20
	v_cvt_pk_bf16_f32 v239, v18, v19
	v_exp_f32_e32 v21, v21
	ds_write_b128 v189, v[156:159] offset:30720
	s_waitcnt lgkmcnt(10)
	v_mfma_f32_32x32x16_bf16 v[32:47], v[198:201], v[246:249], v[32:47]
	v_exp_f32_e32 v22, v22
	v_cvt_pk_bf16_f32 v240, v20, v21
	v_exp_f32_e32 v23, v23
	v_mfma_f32_32x32x16_bf16 v[48:63], v[202:205], v[246:249], v[48:63]
	v_mfma_f32_16x16x32_bf16 v[174:177], v[178:181], v[246:249], v[174:177]
	v_exp_f32_e32 v24, v24
	v_cvt_pk_bf16_f32 v241, v22, v23
	v_exp_f32_e32 v25, v25
	v_mfma_f32_32x32x16_bf16 v[32:47], v[206:209], v[250:253], v[32:47]
	v_exp_f32_e32 v26, v26
	v_cvt_pk_bf16_f32 v242, v24, v25
	v_exp_f32_e32 v27, v27
	v_mfma_f32_32x32x16_bf16 v[48:63], v[234:237], v[250:253], v[48:63]
	v_mfma_f32_16x16x32_bf16 v[174:177], v[178:181], v[250:253], v[174:177]
	v_exp_f32_e32 v28, v28
	v_cvt_pk_bf16_f32 v243, v26, v27
	v_exp_f32_e32 v29, v29
	s_waitcnt lgkmcnt(0)
	s_barrier
	v_mfma_f32_32x32x16_bf16 v[32:47], v[160:163], v[238:241], v[32:47]
	ds_read_b128 v[96:99], v173 offset:21504
	ds_read_b128 v[100:103], v173 offset:21536
	ds_read_b128 v[104:107], v173 offset:21568
	ds_read_b128 v[108:111], v173 offset:21600
	v_exp_f32_e32 v30, v30
	v_cvt_pk_bf16_f32 v244, v28, v29
	v_exp_f32_e32 v31, v31
	v_mfma_f32_32x32x16_bf16 v[48:63], v[164:167], v[238:241], v[48:63]
	v_mfma_f32_16x16x32_bf16 v[174:177], v[178:181], v[238:241], v[174:177]
	ds_read_b128 v[112:115], v173 offset:26112
	ds_read_b128 v[116:119], v173 offset:26144
	ds_read_b128 v[120:123], v173 offset:26176
	ds_read_b128 v[124:127], v173 offset:26208
	v_exp_f32_e32 v0, v0
	v_cvt_pk_bf16_f32 v245, v30, v31
	v_exp_f32_e32 v1, v1
	v_add_u32_e32 v214, 0x2000, v214
	global_load_dwordx4 v[152:155], v214, s[4:5]
	global_load_dwordx4 v[156:159], v214, s[6:7]
	v_mfma_f32_32x32x16_bf16 v[32:47], v[190:193], v[242:245], v[32:47]
	v_exp_f32_e32 v2, v2
	v_cvt_pk_bf16_f32 v246, v0, v1
	v_exp_f32_e32 v3, v3
	ds_read_b64_tr_b16 v[198:199], v183 offset:15360
	ds_read_b64_tr_b16 v[200:201], v183 offset:16896
	v_mfma_f32_32x32x16_bf16 v[48:63], v[194:197], v[242:245], v[48:63]
	v_mfma_f32_16x16x32_bf16 v[174:177], v[178:181], v[242:245], v[174:177]
	v_exp_f32_e32 v4, v4
	v_cvt_pk_bf16_f32 v247, v2, v3
	v_exp_f32_e32 v5, v5
	ds_read_b64_tr_b16 v[202:203], v183 offset:15424
	ds_read_b64_tr_b16 v[204:205], v183 offset:16960
	s_waitcnt lgkmcnt(8)
	v_mfma_f32_32x32x16_bf16 v[80:95], v[96:99], v[128:131], 0
	v_exp_f32_e32 v6, v6
	v_cvt_pk_bf16_f32 v248, v4, v5
	v_exp_f32_e32 v7, v7
	ds_read_b64_tr_b16 v[206:207], v183 offset:18432
	ds_read_b64_tr_b16 v[208:209], v183 offset:19968
	v_mfma_f32_32x32x16_bf16 v[80:95], v[100:103], v[132:135], v[80:95]
	v_exp_f32_e32 v8, v8
	v_cvt_pk_bf16_f32 v249, v6, v7
	v_exp_f32_e32 v9, v9
	ds_read_b64_tr_b16 v[234:235], v183 offset:18496
	ds_read_b64_tr_b16 v[236:237], v183 offset:20032
	v_mfma_f32_32x32x16_bf16 v[80:95], v[104:107], v[136:139], v[80:95]
	v_exp_f32_e32 v10, v10
	v_cvt_pk_bf16_f32 v250, v8, v9
	v_exp_f32_e32 v11, v11
	ds_read_b64_tr_b16 v[160:161], v183 offset:30720
	ds_read_b64_tr_b16 v[162:163], v183 offset:32256
	v_mfma_f32_32x32x16_bf16 v[80:95], v[108:111], v[140:143], v[80:95]
	v_exp_f32_e32 v12, v12
	v_cvt_pk_bf16_f32 v251, v10, v11
	v_exp_f32_e32 v13, v13
	ds_read_b64_tr_b16 v[164:165], v183 offset:30784
	ds_read_b64_tr_b16 v[166:167], v183 offset:32320
	s_waitcnt lgkmcnt(12)
	v_mfma_f32_32x32x16_bf16 v[64:79], v[112:115], v[128:131], 0
	v_exp_f32_e32 v14, v14
	v_cvt_pk_bf16_f32 v252, v12, v13
	v_exp_f32_e32 v15, v15
	ds_read_b64_tr_b16 v[190:191], v183 offset:33792
	ds_read_b64_tr_b16 v[192:193], v183 offset:35328
	v_mfma_f32_32x32x16_bf16 v[64:79], v[116:119], v[132:135], v[64:79]
	v_exp_f32_e32 v80, v80
	v_cvt_pk_bf16_f32 v253, v14, v15
	v_exp_f32_e32 v81, v81
	ds_read_b64_tr_b16 v[194:195], v183 offset:33856
	ds_read_b64_tr_b16 v[196:197], v183 offset:35392
	v_mfma_f32_32x32x16_bf16 v[64:79], v[120:123], v[136:139], v[64:79]
	v_exp_f32_e32 v82, v82
	v_cvt_pk_bf16_f32 v238, v80, v81
	v_exp_f32_e32 v83, v83
	s_waitcnt vmcnt(2)
	ds_write_b128 v186, v[144:147]
	v_mfma_f32_32x32x16_bf16 v[64:79], v[124:127], v[140:143], v[64:79]
	v_exp_f32_e32 v84, v84
	v_cvt_pk_bf16_f32 v239, v82, v83
	v_exp_f32_e32 v85, v85
	ds_write_b128 v188, v[148:151] offset:9216
	s_waitcnt lgkmcnt(10)
	v_mfma_f32_32x32x16_bf16 v[32:47], v[198:201], v[246:249], v[32:47]
	v_exp_f32_e32 v86, v86
	v_cvt_pk_bf16_f32 v240, v84, v85
	v_exp_f32_e32 v87, v87
	v_mfma_f32_32x32x16_bf16 v[48:63], v[202:205], v[246:249], v[48:63]
	v_mfma_f32_16x16x32_bf16 v[174:177], v[178:181], v[246:249], v[174:177]
	v_exp_f32_e32 v88, v88
	v_cvt_pk_bf16_f32 v241, v86, v87
	v_exp_f32_e32 v89, v89
	v_mfma_f32_32x32x16_bf16 v[32:47], v[206:209], v[250:253], v[32:47]
	v_exp_f32_e32 v90, v90
	v_cvt_pk_bf16_f32 v242, v88, v89
	v_exp_f32_e32 v91, v91
	v_mfma_f32_32x32x16_bf16 v[48:63], v[234:237], v[250:253], v[48:63]
	v_mfma_f32_16x16x32_bf16 v[174:177], v[178:181], v[250:253], v[174:177]
	v_exp_f32_e32 v92, v92
	v_cvt_pk_bf16_f32 v243, v90, v91
	v_exp_f32_e32 v93, v93
	s_waitcnt lgkmcnt(0)
	s_barrier
	v_mfma_f32_32x32x16_bf16 v[32:47], v[160:163], v[238:241], v[32:47]
	ds_read_b128 v[96:99], v172
	ds_read_b128 v[100:103], v172 offset:32
	ds_read_b128 v[104:107], v172 offset:64
	ds_read_b128 v[108:111], v172 offset:96
	v_exp_f32_e32 v94, v94
	v_cvt_pk_bf16_f32 v244, v92, v93
	v_exp_f32_e32 v95, v95
	v_mfma_f32_32x32x16_bf16 v[48:63], v[164:167], v[238:241], v[48:63]
	v_mfma_f32_16x16x32_bf16 v[174:177], v[178:181], v[238:241], v[174:177]
	ds_read_b128 v[112:115], v172 offset:4608
	ds_read_b128 v[116:119], v172 offset:4640
	ds_read_b128 v[120:123], v172 offset:4672
	ds_read_b128 v[124:127], v172 offset:4704
	v_exp_f32_e32 v64, v64
	v_cvt_pk_bf16_f32 v245, v94, v95
	v_exp_f32_e32 v65, v65
	v_add_u32_e32 v214, 0x2000, v214
	global_load_dwordx4 v[144:147], v214, s[4:5]
	global_load_dwordx4 v[148:151], v214, s[6:7]
	v_mfma_f32_32x32x16_bf16 v[32:47], v[190:193], v[242:245], v[32:47]
	v_exp_f32_e32 v66, v66
	v_cvt_pk_bf16_f32 v246, v64, v65
	v_exp_f32_e32 v67, v67
	ds_read_b64_tr_b16 v[198:199], v183 offset:36864
	ds_read_b64_tr_b16 v[200:201], v183 offset:38400
	v_mfma_f32_32x32x16_bf16 v[48:63], v[194:197], v[242:245], v[48:63]
	v_mfma_f32_16x16x32_bf16 v[174:177], v[178:181], v[242:245], v[174:177]
	v_exp_f32_e32 v68, v68
	v_cvt_pk_bf16_f32 v247, v66, v67
	v_exp_f32_e32 v69, v69
	ds_read_b64_tr_b16 v[202:203], v183 offset:36928
	ds_read_b64_tr_b16 v[204:205], v183 offset:38464
	s_waitcnt lgkmcnt(8)
	v_mfma_f32_32x32x16_bf16 v[16:31], v[96:99], v[128:131], 0
	v_exp_f32_e32 v70, v70
	v_cvt_pk_bf16_f32 v248, v68, v69
	v_exp_f32_e32 v71, v71
	ds_read_b64_tr_b16 v[206:207], v183 offset:39936
	ds_read_b64_tr_b16 v[208:209], v183 offset:41472
	v_mfma_f32_32x32x16_bf16 v[16:31], v[100:103], v[132:135], v[16:31]
	v_exp_f32_e32 v72, v72
	v_cvt_pk_bf16_f32 v249, v70, v71
	v_exp_f32_e32 v73, v73
	ds_read_b64_tr_b16 v[234:235], v183 offset:40000
	ds_read_b64_tr_b16 v[236:237], v183 offset:41536
	v_mfma_f32_32x32x16_bf16 v[16:31], v[104:107], v[136:139], v[16:31]
	v_exp_f32_e32 v74, v74
	v_cvt_pk_bf16_f32 v250, v72, v73
	v_exp_f32_e32 v75, v75
	ds_read_b64_tr_b16 v[160:161], v182 offset:9216
	ds_read_b64_tr_b16 v[162:163], v182 offset:10752
	v_mfma_f32_32x32x16_bf16 v[16:31], v[108:111], v[140:143], v[16:31]
	v_exp_f32_e32 v76, v76
	v_cvt_pk_bf16_f32 v251, v74, v75
	v_exp_f32_e32 v77, v77
	ds_read_b64_tr_b16 v[164:165], v182 offset:9280
	ds_read_b64_tr_b16 v[166:167], v182 offset:10816
	s_waitcnt lgkmcnt(12)
	v_mfma_f32_32x32x16_bf16 v[0:15], v[112:115], v[128:131], 0
	v_exp_f32_e32 v78, v78
	v_cvt_pk_bf16_f32 v252, v76, v77
	v_exp_f32_e32 v79, v79
	ds_read_b64_tr_b16 v[190:191], v182 offset:12288
	ds_read_b64_tr_b16 v[192:193], v182 offset:13824
	v_mfma_f32_32x32x16_bf16 v[0:15], v[116:119], v[132:135], v[0:15]
	v_exp_f32_e32 v16, v16
	v_cvt_pk_bf16_f32 v253, v78, v79
	v_exp_f32_e32 v17, v17
	ds_read_b64_tr_b16 v[194:195], v182 offset:12352
	ds_read_b64_tr_b16 v[196:197], v182 offset:13888
	v_mfma_f32_32x32x16_bf16 v[0:15], v[120:123], v[136:139], v[0:15]
	v_exp_f32_e32 v18, v18
	v_cvt_pk_bf16_f32 v238, v16, v17
	v_exp_f32_e32 v19, v19
	s_waitcnt vmcnt(2)
	ds_write_b128 v186, v[152:155] offset:21504
	v_mfma_f32_32x32x16_bf16 v[0:15], v[124:127], v[140:143], v[0:15]
	v_exp_f32_e32 v20, v20
	v_cvt_pk_bf16_f32 v239, v18, v19
	v_exp_f32_e32 v21, v21
	ds_write_b128 v188, v[156:159] offset:30720
	s_waitcnt lgkmcnt(10)
	v_mfma_f32_32x32x16_bf16 v[32:47], v[198:201], v[246:249], v[32:47]
	v_exp_f32_e32 v22, v22
	v_cvt_pk_bf16_f32 v240, v20, v21
	v_exp_f32_e32 v23, v23
	v_mfma_f32_32x32x16_bf16 v[48:63], v[202:205], v[246:249], v[48:63]
	v_mfma_f32_16x16x32_bf16 v[174:177], v[178:181], v[246:249], v[174:177]
	v_exp_f32_e32 v24, v24
	v_cvt_pk_bf16_f32 v241, v22, v23
	v_exp_f32_e32 v25, v25
	v_mfma_f32_32x32x16_bf16 v[32:47], v[206:209], v[250:253], v[32:47]
	v_exp_f32_e32 v26, v26
	v_cvt_pk_bf16_f32 v242, v24, v25
	v_exp_f32_e32 v27, v27
	v_mfma_f32_32x32x16_bf16 v[48:63], v[234:237], v[250:253], v[48:63]
	v_mfma_f32_16x16x32_bf16 v[174:177], v[178:181], v[250:253], v[174:177]
	v_exp_f32_e32 v28, v28
	v_cvt_pk_bf16_f32 v243, v26, v27
	v_exp_f32_e32 v29, v29
	s_add_i32 s11, s11, -1
	s_cmp_lg_u32 s11, 0
	s_waitcnt lgkmcnt(0)
	s_barrier
	s_cbranch_scc1 .Lmixb_loop
	v_mfma_f32_32x32x16_bf16 v[32:47], v[160:163], v[238:241], v[32:47]
	ds_read_b128 v[96:99], v172 offset:21504
	ds_read_b128 v[100:103], v172 offset:21536
	ds_read_b128 v[104:107], v172 offset:21568
	ds_read_b128 v[108:111], v172 offset:21600
	v_exp_f32_e32 v30, v30
	v_cvt_pk_bf16_f32 v244, v28, v29
	v_exp_f32_e32 v31, v31
	v_mfma_f32_32x32x16_bf16 v[48:63], v[164:167], v[238:241], v[48:63]
	v_mfma_f32_16x16x32_bf16 v[174:177], v[178:181], v[238:241], v[174:177]
	ds_read_b128 v[112:115], v172 offset:26112
	ds_read_b128 v[116:119], v172 offset:26144
	ds_read_b128 v[120:123], v172 offset:26176
	ds_read_b128 v[124:127], v172 offset:26208
	v_exp_f32_e32 v0, v0
	v_cvt_pk_bf16_f32 v245, v30, v31
	v_exp_f32_e32 v1, v1
	v_add_u32_e32 v214, 0x2000, v214
	global_load_dwordx4 v[152:155], v214, s[4:5]
	global_load_dwordx4 v[156:159], v214, s[6:7]
	v_mfma_f32_32x32x16_bf16 v[32:47], v[190:193], v[242:245], v[32:47]
	v_exp_f32_e32 v2, v2
	v_cvt_pk_bf16_f32 v246, v0, v1
	v_exp_f32_e32 v3, v3
	ds_read_b64_tr_b16 v[198:199], v182 offset:15360
	ds_read_b64_tr_b16 v[200:201], v182 offset:16896
	v_mfma_f32_32x32x16_bf16 v[48:63], v[194:197], v[242:245], v[48:63]
	v_mfma_f32_16x16x32_bf16 v[174:177], v[178:181], v[242:245], v[174:177]
	v_exp_f32_e32 v4, v4
	v_cvt_pk_bf16_f32 v247, v2, v3
	v_exp_f32_e32 v5, v5
	ds_read_b64_tr_b16 v[202:203], v182 offset:15424
	ds_read_b64_tr_b16 v[204:205], v182 offset:16960
	s_waitcnt lgkmcnt(8)
	v_mfma_f32_32x32x16_bf16 v[80:95], v[96:99], v[128:131], 0
	v_exp_f32_e32 v6, v6
	v_cvt_pk_bf16_f32 v248, v4, v5
	v_exp_f32_e32 v7, v7
	ds_read_b64_tr_b16 v[206:207], v182 offset:18432
	ds_read_b64_tr_b16 v[208:209], v182 offset:19968
	v_mfma_f32_32x32x16_bf16 v[80:95], v[100:103], v[132:135], v[80:95]
	v_exp_f32_e32 v8, v8
	v_cvt_pk_bf16_f32 v249, v6, v7
	v_exp_f32_e32 v9, v9
	ds_read_b64_tr_b16 v[234:235], v182 offset:18496
	ds_read_b64_tr_b16 v[236:237], v182 offset:20032
	v_mfma_f32_32x32x16_bf16 v[80:95], v[104:107], v[136:139], v[80:95]
	v_exp_f32_e32 v10, v10
	v_cvt_pk_bf16_f32 v250, v8, v9
	v_exp_f32_e32 v11, v11
	ds_read_b64_tr_b16 v[160:161], v182 offset:30720
	ds_read_b64_tr_b16 v[162:163], v182 offset:32256
	v_mfma_f32_32x32x16_bf16 v[80:95], v[108:111], v[140:143], v[80:95]
	v_exp_f32_e32 v12, v12
	v_cvt_pk_bf16_f32 v251, v10, v11
	v_exp_f32_e32 v13, v13
	ds_read_b64_tr_b16 v[164:165], v182 offset:30784
	ds_read_b64_tr_b16 v[166:167], v182 offset:32320
	s_waitcnt lgkmcnt(12)
	v_mfma_f32_32x32x16_bf16 v[64:79], v[112:115], v[128:131], 0
	v_exp_f32_e32 v14, v14
	v_cvt_pk_bf16_f32 v252, v12, v13
	v_exp_f32_e32 v15, v15
	ds_read_b64_tr_b16 v[190:191], v182 offset:33792
	ds_read_b64_tr_b16 v[192:193], v182 offset:35328
	v_mfma_f32_32x32x16_bf16 v[64:79], v[116:119], v[132:135], v[64:79]
	v_exp_f32_e32 v80, v80
	v_cvt_pk_bf16_f32 v253, v14, v15
	v_exp_f32_e32 v81, v81
	ds_read_b64_tr_b16 v[194:195], v182 offset:33856
	ds_read_b64_tr_b16 v[196:197], v182 offset:35392
	v_mfma_f32_32x32x16_bf16 v[64:79], v[120:123], v[136:139], v[64:79]
	v_exp_f32_e32 v82, v82
	v_cvt_pk_bf16_f32 v238, v80, v81
	v_exp_f32_e32 v83, v83
	s_waitcnt vmcnt(2)
	ds_write_b128 v187, v[144:147]
	v_mfma_f32_32x32x16_bf16 v[64:79], v[124:127], v[140:143], v[64:79]
	v_exp_f32_e32 v84, v84
	v_cvt_pk_bf16_f32 v239, v82, v83
	v_exp_f32_e32 v85, v85
	ds_write_b128 v189, v[148:151] offset:9216
	s_waitcnt lgkmcnt(10)
	v_mfma_f32_32x32x16_bf16 v[32:47], v[198:201], v[246:249], v[32:47]
	v_exp_f32_e32 v86, v86
	v_cvt_pk_bf16_f32 v240, v84, v85
	v_exp_f32_e32 v87, v87
	v_mfma_f32_32x32x16_bf16 v[48:63], v[202:205], v[246:249], v[48:63]
	v_mfma_f32_16x16x32_bf16 v[174:177], v[178:181], v[246:249], v[174:177]
	v_exp_f32_e32 v88, v88
	v_cvt_pk_bf16_f32 v241, v86, v87
	v_exp_f32_e32 v89, v89
	v_mfma_f32_32x32x16_bf16 v[32:47], v[206:209], v[250:253], v[32:47]
	v_exp_f32_e32 v90, v90
	v_cvt_pk_bf16_f32 v242, v88, v89
	v_exp_f32_e32 v91, v91
	v_mfma_f32_32x32x16_bf16 v[48:63], v[234:237], v[250:253], v[48:63]
	v_mfma_f32_16x16x32_bf16 v[174:177], v[178:181], v[250:253], v[174:177]
	v_exp_f32_e32 v92, v92
	v_cvt_pk_bf16_f32 v243, v90, v91
	v_exp_f32_e32 v93, v93
	s_waitcnt lgkmcnt(0)
	s_barrier
	v_mfma_f32_32x32x16_bf16 v[32:47], v[160:163], v[238:241], v[32:47]
	ds_read_b128 v[96:99], v173
	ds_read_b128 v[100:103], v173 offset:32
	ds_read_b128 v[104:107], v173 offset:64
	ds_read_b128 v[108:111], v173 offset:96
	v_exp_f32_e32 v94, v94
	v_cvt_pk_bf16_f32 v244, v92, v93
	v_exp_f32_e32 v95, v95
	v_mfma_f32_32x32x16_bf16 v[48:63], v[164:167], v[238:241], v[48:63]
	v_mfma_f32_16x16x32_bf16 v[174:177], v[178:181], v[238:241], v[174:177]
	ds_read_b128 v[112:115], v173 offset:4608
	ds_read_b128 v[116:119], v173 offset:4640
	ds_read_b128 v[120:123], v173 offset:4672
	ds_read_b128 v[124:127], v173 offset:4704
	v_exp_f32_e32 v64, v64
	v_cvt_pk_bf16_f32 v245, v94, v95
	v_exp_f32_e32 v65, v65
	s_nop 0
	v_mfma_f32_32x32x16_bf16 v[32:47], v[190:193], v[242:245], v[32:47]
	v_exp_f32_e32 v66, v66
	v_cvt_pk_bf16_f32 v246, v64, v65
	v_exp_f32_e32 v67, v67
	ds_read_b64_tr_b16 v[198:199], v182 offset:36864
	ds_read_b64_tr_b16 v[200:201], v182 offset:38400
	v_mfma_f32_32x32x16_bf16 v[48:63], v[194:197], v[242:245], v[48:63]
	v_mfma_f32_16x16x32_bf16 v[174:177], v[178:181], v[242:245], v[174:177]
	v_exp_f32_e32 v68, v68
	v_cvt_pk_bf16_f32 v247, v66, v67
	v_exp_f32_e32 v69, v69
	ds_read_b64_tr_b16 v[202:203], v182 offset:36928
	ds_read_b64_tr_b16 v[204:205], v182 offset:38464
	s_waitcnt lgkmcnt(8)
	v_mfma_f32_32x32x16_bf16 v[16:31], v[96:99], v[128:131], 0
	v_exp_f32_e32 v70, v70
	v_cvt_pk_bf16_f32 v248, v68, v69
	v_exp_f32_e32 v71, v71
	ds_read_b64_tr_b16 v[206:207], v182 offset:39936
	ds_read_b64_tr_b16 v[208:209], v182 offset:41472
	v_mfma_f32_32x32x16_bf16 v[16:31], v[100:103], v[132:135], v[16:31]
	v_exp_f32_e32 v72, v72
	v_cvt_pk_bf16_f32 v249, v70, v71
	v_exp_f32_e32 v73, v73
	ds_read_b64_tr_b16 v[234:235], v182 offset:40000
	ds_read_b64_tr_b16 v[236:237], v182 offset:41536
	v_mfma_f32_32x32x16_bf16 v[16:31], v[104:107], v[136:139], v[16:31]
	v_exp_f32_e32 v74, v74
	v_cvt_pk_bf16_f32 v250, v72, v73
	v_exp_f32_e32 v75, v75
	ds_read_b64_tr_b16 v[160:161], v183 offset:9216
	ds_read_b64_tr_b16 v[162:163], v183 offset:10752
	v_mfma_f32_32x32x16_bf16 v[16:31], v[108:111], v[140:143], v[16:31]
	v_exp_f32_e32 v76, v76
	v_cvt_pk_bf16_f32 v251, v74, v75
	v_exp_f32_e32 v77, v77
	ds_read_b64_tr_b16 v[164:165], v183 offset:9280
	ds_read_b64_tr_b16 v[166:167], v183 offset:10816
	s_waitcnt lgkmcnt(12)
	v_mfma_f32_32x32x16_bf16 v[0:15], v[112:115], v[128:131], 0
	v_exp_f32_e32 v78, v78
	v_cvt_pk_bf16_f32 v252, v76, v77
	v_exp_f32_e32 v79, v79
	ds_read_b64_tr_b16 v[190:191], v183 offset:12288
	ds_read_b64_tr_b16 v[192:193], v183 offset:13824
	v_mfma_f32_32x32x16_bf16 v[0:15], v[116:119], v[132:135], v[0:15]
	v_exp_f32_e32 v16, v16
	v_cvt_pk_bf16_f32 v253, v78, v79
	v_exp_f32_e32 v17, v17
	ds_read_b64_tr_b16 v[194:195], v183 offset:12352
	ds_read_b64_tr_b16 v[196:197], v183 offset:13888
	v_mfma_f32_32x32x16_bf16 v[0:15], v[120:123], v[136:139], v[0:15]
	v_exp_f32_e32 v18, v18
	v_cvt_pk_bf16_f32 v238, v16, v17
	v_exp_f32_e32 v19, v19
	s_waitcnt vmcnt(0)
	ds_write_b128 v187, v[152:155] offset:21504
	v_mfma_f32_32x32x16_bf16 v[0:15], v[124:127], v[140:143], v[0:15]
	v_exp_f32_e32 v20, v20
	v_cvt_pk_bf16_f32 v239, v18, v19
	v_exp_f32_e32 v21, v21
	ds_write_b128 v189, v[156:159] offset:30720
	s_waitcnt lgkmcnt(10)
	v_mfma_f32_32x32x16_bf16 v[32:47], v[198:201], v[246:249], v[32:47]
	v_exp_f32_e32 v22, v22
	v_cvt_pk_bf16_f32 v240, v20, v21
	v_exp_f32_e32 v23, v23
	v_mfma_f32_32x32x16_bf16 v[48:63], v[202:205], v[246:249], v[48:63]
	v_mfma_f32_16x16x32_bf16 v[174:177], v[178:181], v[246:249], v[174:177]
	v_exp_f32_e32 v24, v24
	v_cvt_pk_bf16_f32 v241, v22, v23
	v_exp_f32_e32 v25, v25
	v_mfma_f32_32x32x16_bf16 v[32:47], v[206:209], v[250:253], v[32:47]
	v_exp_f32_e32 v26, v26
	v_cvt_pk_bf16_f32 v242, v24, v25
	v_exp_f32_e32 v27, v27
	v_mfma_f32_32x32x16_bf16 v[48:63], v[234:237], v[250:253], v[48:63]
	v_mfma_f32_16x16x32_bf16 v[174:177], v[178:181], v[250:253], v[174:177]
	v_exp_f32_e32 v28, v28
	v_cvt_pk_bf16_f32 v243, v26, v27
	v_exp_f32_e32 v29, v29
	s_waitcnt lgkmcnt(0)
	s_barrier
; __device__ __forceinline__ void attnB_unit(LAS unsigned char* lds, const Args& A, int unit, const float* kng, bool do_store = true) {
;     ...
;     l += (lp[0] + lp[1]) + (lp[2] + lp[3]);
;     l += __shfl_xor(l, 32);
	v_mfma_f32_32x32x16_bf16 v[32:47], v[160:163], v[238:241], v[32:47]
	ds_read_b128 v[96:99], v173 offset:21504
	ds_read_b128 v[100:103], v173 offset:21536
	ds_read_b128 v[104:107], v173 offset:21568
	ds_read_b128 v[108:111], v173 offset:21600
	v_exp_f32_e32 v30, v30
	v_cvt_pk_bf16_f32 v244, v28, v29
	v_exp_f32_e32 v31, v31
	v_mfma_f32_32x32x16_bf16 v[48:63], v[164:167], v[238:241], v[48:63]
	v_mfma_f32_16x16x32_bf16 v[174:177], v[178:181], v[238:241], v[174:177]
	ds_read_b128 v[112:115], v173 offset:26112
	ds_read_b128 v[116:119], v173 offset:26144
	ds_read_b128 v[120:123], v173 offset:26176
	ds_read_b128 v[124:127], v173 offset:26208
	v_exp_f32_e32 v0, v0
	v_cvt_pk_bf16_f32 v245, v30, v31
	v_exp_f32_e32 v1, v1
	s_nop 0
	v_mfma_f32_32x32x16_bf16 v[32:47], v[190:193], v[242:245], v[32:47]
	v_exp_f32_e32 v2, v2
	v_cvt_pk_bf16_f32 v246, v0, v1
	v_exp_f32_e32 v3, v3
	ds_read_b64_tr_b16 v[198:199], v183 offset:15360
	ds_read_b64_tr_b16 v[200:201], v183 offset:16896
	v_mfma_f32_32x32x16_bf16 v[48:63], v[194:197], v[242:245], v[48:63]
	v_mfma_f32_16x16x32_bf16 v[174:177], v[178:181], v[242:245], v[174:177]
	v_exp_f32_e32 v4, v4
	v_cvt_pk_bf16_f32 v247, v2, v3
	v_exp_f32_e32 v5, v5
	ds_read_b64_tr_b16 v[202:203], v183 offset:15424
	ds_read_b64_tr_b16 v[204:205], v183 offset:16960
	s_waitcnt lgkmcnt(8)
	v_mfma_f32_32x32x16_bf16 v[80:95], v[96:99], v[128:131], 0
	v_exp_f32_e32 v6, v6
	v_cvt_pk_bf16_f32 v248, v4, v5
	v_exp_f32_e32 v7, v7
	ds_read_b64_tr_b16 v[206:207], v183 offset:18432
	ds_read_b64_tr_b16 v[208:209], v183 offset:19968
	v_mfma_f32_32x32x16_bf16 v[80:95], v[100:103], v[132:135], v[80:95]
	v_exp_f32_e32 v8, v8
	v_cvt_pk_bf16_f32 v249, v6, v7
	v_exp_f32_e32 v9, v9
	ds_read_b64_tr_b16 v[234:235], v183 offset:18496
	ds_read_b64_tr_b16 v[236:237], v183 offset:20032
	v_mfma_f32_32x32x16_bf16 v[80:95], v[104:107], v[136:139], v[80:95]
	v_exp_f32_e32 v10, v10
	v_cvt_pk_bf16_f32 v250, v8, v9
	v_exp_f32_e32 v11, v11
	ds_read_b64_tr_b16 v[160:161], v183 offset:30720
	ds_read_b64_tr_b16 v[162:163], v183 offset:32256
	v_mfma_f32_32x32x16_bf16 v[80:95], v[108:111], v[140:143], v[80:95]
	v_exp_f32_e32 v12, v12
	v_cvt_pk_bf16_f32 v251, v10, v11
	v_exp_f32_e32 v13, v13
	ds_read_b64_tr_b16 v[164:165], v183 offset:30784
	ds_read_b64_tr_b16 v[166:167], v183 offset:32320
	s_waitcnt lgkmcnt(12)
	v_mfma_f32_32x32x16_bf16 v[64:79], v[112:115], v[128:131], 0
	v_exp_f32_e32 v14, v14
	v_cvt_pk_bf16_f32 v252, v12, v13
	v_exp_f32_e32 v15, v15
	ds_read_b64_tr_b16 v[190:191], v183 offset:33792
	ds_read_b64_tr_b16 v[192:193], v183 offset:35328
	v_mfma_f32_32x32x16_bf16 v[64:79], v[116:119], v[132:135], v[64:79]
	v_exp_f32_e32 v80, v80
	v_cvt_pk_bf16_f32 v253, v14, v15
	v_exp_f32_e32 v81, v81
	ds_read_b64_tr_b16 v[194:195], v183 offset:33856
	ds_read_b64_tr_b16 v[196:197], v183 offset:35392
	v_mfma_f32_32x32x16_bf16 v[64:79], v[120:123], v[136:139], v[64:79]
	v_exp_f32_e32 v82, v82
	v_cvt_pk_bf16_f32 v238, v80, v81
	v_exp_f32_e32 v83, v83
	v_mfma_f32_32x32x16_bf16 v[64:79], v[124:127], v[140:143], v[64:79]
	v_exp_f32_e32 v84, v84
	v_cvt_pk_bf16_f32 v239, v82, v83
	v_exp_f32_e32 v85, v85
	s_waitcnt lgkmcnt(8)
	v_mfma_f32_32x32x16_bf16 v[32:47], v[198:201], v[246:249], v[32:47]
	v_exp_f32_e32 v86, v86
	v_cvt_pk_bf16_f32 v240, v84, v85
	v_exp_f32_e32 v87, v87
	v_mfma_f32_32x32x16_bf16 v[48:63], v[202:205], v[246:249], v[48:63]
	v_mfma_f32_16x16x32_bf16 v[174:177], v[178:181], v[246:249], v[174:177]
	v_exp_f32_e32 v88, v88
	v_cvt_pk_bf16_f32 v241, v86, v87
	v_exp_f32_e32 v89, v89
	v_mfma_f32_32x32x16_bf16 v[32:47], v[206:209], v[250:253], v[32:47]
	v_exp_f32_e32 v90, v90
	v_cvt_pk_bf16_f32 v242, v88, v89
	v_exp_f32_e32 v91, v91
	v_mfma_f32_32x32x16_bf16 v[48:63], v[234:237], v[250:253], v[48:63]
	v_mfma_f32_16x16x32_bf16 v[174:177], v[178:181], v[250:253], v[174:177]
	v_exp_f32_e32 v92, v92
	v_cvt_pk_bf16_f32 v243, v90, v91
	v_exp_f32_e32 v93, v93
	s_waitcnt lgkmcnt(0)
	s_barrier
	v_mfma_f32_32x32x16_bf16 v[32:47], v[160:163], v[238:241], v[32:47]
	v_exp_f32_e32 v94, v94
	v_cvt_pk_bf16_f32 v244, v92, v93
	v_exp_f32_e32 v95, v95
	v_mfma_f32_32x32x16_bf16 v[48:63], v[164:167], v[238:241], v[48:63]
	v_mfma_f32_16x16x32_bf16 v[174:177], v[178:181], v[238:241], v[174:177]
	v_exp_f32_e32 v64, v64
	v_cvt_pk_bf16_f32 v245, v94, v95
	v_exp_f32_e32 v65, v65
	s_nop 0
	v_mfma_f32_32x32x16_bf16 v[32:47], v[190:193], v[242:245], v[32:47]
	v_exp_f32_e32 v66, v66
	v_cvt_pk_bf16_f32 v246, v64, v65
	v_exp_f32_e32 v67, v67
	ds_read_b64_tr_b16 v[198:199], v183 offset:36864
	ds_read_b64_tr_b16 v[200:201], v183 offset:38400
	v_mfma_f32_32x32x16_bf16 v[48:63], v[194:197], v[242:245], v[48:63]
	v_mfma_f32_16x16x32_bf16 v[174:177], v[178:181], v[242:245], v[174:177]
	v_exp_f32_e32 v68, v68
	v_cvt_pk_bf16_f32 v247, v66, v67
	v_exp_f32_e32 v69, v69
	ds_read_b64_tr_b16 v[202:203], v183 offset:36928
	ds_read_b64_tr_b16 v[204:205], v183 offset:38464
	v_exp_f32_e32 v70, v70
	v_cvt_pk_bf16_f32 v248, v68, v69
	v_exp_f32_e32 v71, v71
	ds_read_b64_tr_b16 v[206:207], v183 offset:39936
	ds_read_b64_tr_b16 v[208:209], v183 offset:41472
	v_exp_f32_e32 v72, v72
	v_cvt_pk_bf16_f32 v249, v70, v71
	v_exp_f32_e32 v73, v73
	ds_read_b64_tr_b16 v[234:235], v183 offset:40000
	ds_read_b64_tr_b16 v[236:237], v183 offset:41536
	v_exp_f32_e32 v74, v74
	v_cvt_pk_bf16_f32 v250, v72, v73
	v_exp_f32_e32 v75, v75
	v_exp_f32_e32 v76, v76
	v_cvt_pk_bf16_f32 v251, v74, v75
	v_exp_f32_e32 v77, v77
	v_exp_f32_e32 v78, v78
	v_cvt_pk_bf16_f32 v252, v76, v77
	v_exp_f32_e32 v79, v79
	s_nop 0
	v_cvt_pk_bf16_f32 v253, v78, v79
	s_waitcnt lgkmcnt(0)
	v_mfma_f32_32x32x16_bf16 v[32:47], v[198:201], v[246:249], v[32:47]
	v_mfma_f32_32x32x16_bf16 v[48:63], v[202:205], v[246:249], v[48:63]
	v_mfma_f32_16x16x32_bf16 v[174:177], v[178:181], v[246:249], v[174:177]
	v_mfma_f32_32x32x16_bf16 v[32:47], v[206:209], v[250:253], v[32:47]
	v_mfma_f32_32x32x16_bf16 v[48:63], v[234:237], v[250:253], v[48:63]
	v_mfma_f32_16x16x32_bf16 v[174:177], v[178:181], v[250:253], v[174:177]
	s_nop 7
	v_and_b32_e32 v214, 15, v217
	v_lshlrev_b32_e32 v214, 2, v214
	v_and_b32_e32 v219, 16, v217
	ds_bpermute_b32 v215, v214, v174
	ds_bpermute_b32 v218, v214, v175
	v_cmp_ne_u32_e32 vcc, 0, v219
	s_waitcnt lgkmcnt(0)
	s_nop 1
	v_cndmask_b32_e32 v174, v215, v218, vcc
	v_mul_f32_e32 v174, 0.5, v174
	v_mov_b32_e32 v175, 0
	v_mov_b32_e32 v176, 0
	v_mov_b32_e32 v177, 0
	v_mov_b32_e32 v233, 0
	s_branch .LBB0_275
